# prep: the eight per-(layer,dir) parameter vectors are fetched once per workgroup (one per wave, issued during the LoRA matmul) and shared through LDS
# speedup vs baseline: 1.0151x; 1.0053x over previous
.LBB0_477:
	s_and_b64 s[0:1], s[16:17], exec
	s_movk_i32 s0, 0x380
	s_cselect_b32 s0, s0, 0x400
	v_or_b32_e32 v0, s0, v76
	v_lshl_or_b32 v2, s22, 7, v126
	v_readlane_b32 s60, v253, 46
	v_lshlrev_b32_e32 v128, 1, v0
	v_ashrrev_i32_e32 v3, 31, v2
	v_readlane_b32 s72, v253, 58
	v_readlane_b32 s73, v253, 59
	v_lshl_add_u64 v[0:1], s[4:5], 0, v[128:129]
	s_waitcnt vmcnt(0)
	v_lshl_add_u64 v[2:3], v[2:3], 2, s[72:73]
	s_barrier
	global_load_dword v2, v[2:3], off
	s_cselect_b32 s45, -1, 1
	v_readlane_b32 s61, v253, 47
	v_readlane_b32 s62, v253, 48
	v_readlane_b32 s63, v253, 49
	v_readlane_b32 s64, v253, 50
	v_readlane_b32 s65, v253, 51
	v_readlane_b32 s66, v253, 52
	v_readlane_b32 s67, v253, 53
	v_readlane_b32 s68, v253, 54
	v_readlane_b32 s69, v253, 55
	v_readlane_b32 s70, v253, 56
	v_readlane_b32 s71, v253, 57
	v_readlane_b32 s74, v253, 60
	v_readlane_b32 s75, v253, 61
	v_mov_b32_e32 v3, s45
	v_cndmask_b32_e64 v4, v83, 0, s[16:17]
	v_cmp_eq_u32_e32 vcc, v84, v4
	v_lshl_add_u64 v[4:5], v[0:1], 0, v[40:41]
	global_load_ushort v138, v[4:5], off
	v_cndmask_b32_e64 v4, v3, 0, vcc
	v_cndmask_b32_e64 v16, 1.0, 0, vcc
	v_add_u32_e32 v4, v4, v82
	v_mad_i64_i32 v[4:5], s[0:1], v4, s87, v[0:1]
	global_load_ushort v148, v[4:5], off
	v_cndmask_b32_e64 v4, v87, 0, s[16:17]
	v_cmp_eq_u32_e32 vcc, v88, v4
	v_lshl_add_u64 v[4:5], v[0:1], 0, v[42:43]
	global_load_ushort v139, v[4:5], off
	v_cndmask_b32_e64 v4, v3, 0, vcc
	v_cndmask_b32_e64 v17, 1.0, 0, vcc
	v_add_u32_e32 v4, v4, v86
	v_mad_i64_i32 v[4:5], s[0:1], v4, s87, v[0:1]
	global_load_ushort v149, v[4:5], off
	v_cndmask_b32_e64 v4, v91, 0, s[16:17]
	v_cmp_eq_u32_e32 vcc, v92, v4
	v_lshl_add_u64 v[4:5], v[0:1], 0, v[44:45]
	global_load_ushort v140, v[4:5], off
	v_cndmask_b32_e64 v4, v3, 0, vcc
	v_cndmask_b32_e64 v18, 1.0, 0, vcc
	v_add_u32_e32 v4, v4, v90
	v_mad_i64_i32 v[4:5], s[0:1], v4, s87, v[0:1]
	global_load_ushort v150, v[4:5], off
	v_cndmask_b32_e64 v4, v95, 0, s[16:17]
	v_cmp_eq_u32_e32 vcc, v96, v4
	v_lshl_add_u64 v[4:5], v[0:1], 0, v[46:47]
	global_load_ushort v141, v[4:5], off
	v_cndmask_b32_e64 v4, v3, 0, vcc
	v_cndmask_b32_e64 v19, 1.0, 0, vcc
	v_add_u32_e32 v4, v4, v94
	v_mad_i64_i32 v[4:5], s[0:1], v4, s87, v[0:1]
	global_load_ushort v151, v[4:5], off
	v_cndmask_b32_e64 v4, v99, 0, s[16:17]
	v_cmp_eq_u32_e32 vcc, v100, v4
	v_lshl_add_u64 v[4:5], v[0:1], 0, v[48:49]
	global_load_ushort v142, v[4:5], off
	v_cndmask_b32_e64 v4, v3, 0, vcc
	v_cndmask_b32_e64 v20, 1.0, 0, vcc
	v_add_u32_e32 v4, v4, v98
	v_mad_i64_i32 v[4:5], s[0:1], v4, s87, v[0:1]
	global_load_ushort v152, v[4:5], off
	v_cndmask_b32_e64 v4, v103, 0, s[16:17]
	v_cmp_eq_u32_e32 vcc, v104, v4
	v_lshl_add_u64 v[4:5], v[0:1], 0, v[50:51]
	global_load_ushort v143, v[4:5], off
	v_cndmask_b32_e64 v4, v3, 0, vcc
	v_cndmask_b32_e64 v21, 1.0, 0, vcc
	v_add_u32_e32 v4, v4, v102
	v_mad_i64_i32 v[4:5], s[0:1], v4, s87, v[0:1]
	global_load_ushort v153, v[4:5], off
	v_cndmask_b32_e64 v4, v107, 0, s[16:17]
	v_cmp_eq_u32_e32 vcc, v108, v4
	v_lshl_add_u64 v[4:5], v[0:1], 0, v[52:53]
	global_load_ushort v144, v[4:5], off
	v_cndmask_b32_e64 v4, v3, 0, vcc
	v_cndmask_b32_e64 v22, 1.0, 0, vcc
	v_add_u32_e32 v4, v4, v106
	v_mad_i64_i32 v[4:5], s[0:1], v4, s87, v[0:1]
	global_load_ushort v154, v[4:5], off
	v_cndmask_b32_e64 v4, v111, 0, s[16:17]
	v_cmp_eq_u32_e32 vcc, v112, v4
	v_lshl_add_u64 v[4:5], v[0:1], 0, v[54:55]
	global_load_ushort v145, v[4:5], off
	v_cndmask_b32_e64 v4, v3, 0, vcc
	v_cndmask_b32_e64 v23, 1.0, 0, vcc
	v_add_u32_e32 v4, v4, v110
	v_mad_i64_i32 v[4:5], s[0:1], v4, s87, v[0:1]
	global_load_ushort v155, v[4:5], off
	v_cndmask_b32_e64 v4, v115, 0, s[16:17]
	v_cmp_eq_u32_e32 vcc, v116, v4
	v_lshl_add_u64 v[4:5], v[0:1], 0, v[56:57]
	global_load_ushort v146, v[4:5], off
	v_cndmask_b32_e64 v4, v3, 0, vcc
	v_cndmask_b32_e64 v24, 1.0, 0, vcc
	v_add_u32_e32 v4, v4, v114
	v_mad_i64_i32 v[4:5], s[0:1], v4, s87, v[0:1]
	global_load_ushort v156, v[4:5], off
	v_cndmask_b32_e64 v4, v119, 0, s[16:17]
	v_cmp_eq_u32_e32 vcc, v120, v4
	v_lshl_add_u64 v[4:5], v[0:1], 0, v[58:59]
	global_load_ushort v147, v[4:5], off
	v_cndmask_b32_e64 v4, v3, 0, vcc
	v_cndmask_b32_e64 v25, 1.0, 0, vcc
	v_add_u32_e32 v4, v4, v118
	v_mad_i64_i32 v[4:5], s[0:1], v4, s87, v[0:1]
	global_load_ushort v157, v[4:5], off
	s_waitcnt vmcnt(0)
	v_lshlrev_b32_e32 v6, 16, v138
	v_lshlrev_b32_e32 v7, 16, v139
	v_lshlrev_b32_e32 v4, 16, v148
	v_lshlrev_b32_e32 v5, 16, v149
	v_fma_f32 v4, v16, v4, -v6
	v_fma_f32 v5, v17, v5, -v7
	v_fmac_f32_e32 v6, v2, v4
	v_fmac_f32_e32 v7, v2, v5
	v_add_f32_e32 v4, v6, v6
	v_add_f32_e32 v5, v7, v7
	v_mul_f32_e32 v4, 0x3fb8aa3b, v4
	v_mul_f32_e32 v5, 0x3fb8aa3b, v5
	v_exp_f32_e32 v4, v4
	v_exp_f32_e32 v5, v5
	s_nop 0
	v_add_f32_e32 v4, 1.0, v4
	v_add_f32_e32 v5, 1.0, v5
	v_rcp_f32_e32 v4, v4
	v_rcp_f32_e32 v5, v5
	s_nop 0
	v_fma_f32 v4, v4, -2.0, 1.0
	v_fma_f32 v5, v5, -2.0, 1.0
	v_cndmask_b32_e64 v4, v6, v4, s[36:37]
	v_cndmask_b32_e64 v5, v7, v5, s[36:37]
	v_cvt_pk_bf16_f32 v4, v4, s0
	v_cvt_pk_bf16_f32 v5, v5, s0
	ds_write_b16 v85, v4
	ds_write_b16 v89, v5
	v_lshlrev_b32_e32 v6, 16, v140
	v_lshlrev_b32_e32 v7, 16, v141
	v_lshlrev_b32_e32 v4, 16, v150
	v_lshlrev_b32_e32 v5, 16, v151
	v_fma_f32 v4, v18, v4, -v6
	v_fma_f32 v5, v19, v5, -v7
	v_fmac_f32_e32 v6, v2, v4
	v_fmac_f32_e32 v7, v2, v5
	v_add_f32_e32 v4, v6, v6
	v_add_f32_e32 v5, v7, v7
	v_mul_f32_e32 v4, 0x3fb8aa3b, v4
	v_mul_f32_e32 v5, 0x3fb8aa3b, v5
	v_exp_f32_e32 v4, v4
	v_exp_f32_e32 v5, v5
	s_nop 0
	v_add_f32_e32 v4, 1.0, v4
	v_add_f32_e32 v5, 1.0, v5
	v_rcp_f32_e32 v4, v4
	v_rcp_f32_e32 v5, v5
	s_nop 0
	v_fma_f32 v4, v4, -2.0, 1.0
	v_fma_f32 v5, v5, -2.0, 1.0
	v_cndmask_b32_e64 v4, v6, v4, s[36:37]
	v_cndmask_b32_e64 v5, v7, v5, s[36:37]
	v_cvt_pk_bf16_f32 v4, v4, s0
	v_cvt_pk_bf16_f32 v5, v5, s0
	ds_write_b16 v93, v4
	ds_write_b16 v97, v5
	v_lshlrev_b32_e32 v6, 16, v142
	v_lshlrev_b32_e32 v7, 16, v143
	v_lshlrev_b32_e32 v4, 16, v152
	v_lshlrev_b32_e32 v5, 16, v153
	v_fma_f32 v4, v20, v4, -v6
	v_fma_f32 v5, v21, v5, -v7
	v_fmac_f32_e32 v6, v2, v4
	v_fmac_f32_e32 v7, v2, v5
	v_add_f32_e32 v4, v6, v6
	v_add_f32_e32 v5, v7, v7
	v_mul_f32_e32 v4, 0x3fb8aa3b, v4
	v_mul_f32_e32 v5, 0x3fb8aa3b, v5
	v_exp_f32_e32 v4, v4
	v_exp_f32_e32 v5, v5
	s_nop 0
	v_add_f32_e32 v4, 1.0, v4
	v_add_f32_e32 v5, 1.0, v5
	v_rcp_f32_e32 v4, v4
	v_rcp_f32_e32 v5, v5
	s_nop 0
	v_fma_f32 v4, v4, -2.0, 1.0
	v_fma_f32 v5, v5, -2.0, 1.0
	v_cndmask_b32_e64 v4, v6, v4, s[36:37]
	v_cndmask_b32_e64 v5, v7, v5, s[36:37]
	v_cvt_pk_bf16_f32 v4, v4, s0
	v_cvt_pk_bf16_f32 v5, v5, s0
	ds_write_b16 v101, v4
	ds_write_b16 v105, v5
	v_lshlrev_b32_e32 v6, 16, v144
	v_lshlrev_b32_e32 v7, 16, v145
	v_lshlrev_b32_e32 v4, 16, v154
	v_lshlrev_b32_e32 v5, 16, v155
	v_fma_f32 v4, v22, v4, -v6
	v_fma_f32 v5, v23, v5, -v7
	v_fmac_f32_e32 v6, v2, v4
	v_fmac_f32_e32 v7, v2, v5
	v_add_f32_e32 v4, v6, v6
	v_add_f32_e32 v5, v7, v7
	v_mul_f32_e32 v4, 0x3fb8aa3b, v4
	v_mul_f32_e32 v5, 0x3fb8aa3b, v5
	v_exp_f32_e32 v4, v4
	v_exp_f32_e32 v5, v5
	s_nop 0
	v_add_f32_e32 v4, 1.0, v4
	v_add_f32_e32 v5, 1.0, v5
	v_rcp_f32_e32 v4, v4
	v_rcp_f32_e32 v5, v5
	s_nop 0
	v_fma_f32 v4, v4, -2.0, 1.0
	v_fma_f32 v5, v5, -2.0, 1.0
	v_cndmask_b32_e64 v4, v6, v4, s[36:37]
	v_cndmask_b32_e64 v5, v7, v5, s[36:37]
	v_cvt_pk_bf16_f32 v4, v4, s0
	v_cvt_pk_bf16_f32 v5, v5, s0
	ds_write_b16 v109, v4
	ds_write_b16 v113, v5
	v_lshlrev_b32_e32 v6, 16, v146
	v_lshlrev_b32_e32 v7, 16, v147
	v_lshlrev_b32_e32 v4, 16, v156
	v_lshlrev_b32_e32 v5, 16, v157
	v_fma_f32 v4, v24, v4, -v6
	v_fma_f32 v5, v25, v5, -v7
	v_fmac_f32_e32 v6, v2, v4
	v_fmac_f32_e32 v7, v2, v5
	v_add_f32_e32 v4, v6, v6
	v_add_f32_e32 v5, v7, v7
	v_mul_f32_e32 v4, 0x3fb8aa3b, v4
	v_mul_f32_e32 v5, 0x3fb8aa3b, v5
	v_exp_f32_e32 v4, v4
	v_exp_f32_e32 v5, v5
	s_nop 0
	v_add_f32_e32 v4, 1.0, v4
	v_add_f32_e32 v5, 1.0, v5
	v_rcp_f32_e32 v4, v4
	v_rcp_f32_e32 v5, v5
	s_nop 0
	v_fma_f32 v4, v4, -2.0, 1.0
	v_fma_f32 v5, v5, -2.0, 1.0
	v_cndmask_b32_e64 v4, v6, v4, s[36:37]
	v_cndmask_b32_e64 v5, v7, v5, s[36:37]
	v_cvt_pk_bf16_f32 v4, v4, s0
	v_cvt_pk_bf16_f32 v5, v5, s0
	ds_write_b16 v117, v4
	ds_write_b16 v121, v5
	s_or_b32 s0, s22, s33
	s_ashr_i32 s1, s0, 31
	s_lshl_b64 s[6:7], s[0:1], 15
	v_lshl_add_u64 v[72:73], v[64:65], 0, s[6:7]
	s_mov_b64 s[6:7], 0x17bce000
	v_lshl_add_u64 v[74:75], v[72:73], 0, s[6:7]
	v_lshl_add_u64 v[134:135], v[74:75], 0, v[60:61]
	s_waitcnt lgkmcnt(0)
	s_barrier
	v_readlane_b32 s10, v254, 34
	v_readlane_b32 s8, v254, 30
	v_readlane_b32 s9, v254, 31
	s_sub_u32 s8, s8, 0x110
	s_subb_u32 s9, s9, 0
	s_load_dwordx2 s[12:13], s[8:9], 0x68
	s_load_dwordx2 s[14:15], s[8:9], 0x78
	s_load_dwordx2 s[28:29], s[8:9], 0x88
	s_load_dwordx4 s[76:79], s[8:9], 0xa0
	s_load_dwordx2 s[80:81], s[8:9], 0xb0
	ds_read_b128 v[28:31], v77
	ds_read_b128 v[24:27], v77 offset:32
	ds_read_b128 v[20:23], v77 offset:64
	ds_read_b128 v[16:19], v77 offset:96
	global_load_dwordx4 v[0:3], v[134:135], off
	global_load_dwordx4 v[138:141], v[134:135], off offset:32
	s_waitcnt vmcnt(1) lgkmcnt(3)
	v_mfma_f32_32x32x16_bf16 v[0:15], v[28:31], v[0:3], 0
	s_waitcnt vmcnt(0) lgkmcnt(2)
	v_mfma_f32_32x32x16_bf16 v[0:15], v[24:27], v[138:141], v[0:15]
	global_load_dwordx4 v[138:141], v[134:135], off offset:64
	s_waitcnt vmcnt(0) lgkmcnt(1)
	v_mfma_f32_32x32x16_bf16 v[0:15], v[20:23], v[138:141], v[0:15]
	global_load_dwordx4 v[138:141], v[134:135], off offset:96
	s_waitcnt vmcnt(0) lgkmcnt(0)
	v_mfma_f32_32x32x16_bf16 v[0:15], v[16:19], v[138:141], v[0:15]
	s_nop 11
	ds_write2st64_b32 v122, v0, v1 offset0:34 offset1:38
	ds_write2st64_b32 v122, v2, v3 offset0:42 offset1:46
	ds_write2st64_b32 v122, v4, v5 offset0:66 offset1:70
	ds_write2st64_b32 v122, v6, v7 offset0:74 offset1:78
	s_and_saveexec_b64 s[6:7], s[38:39]
	s_cbranch_execz .LBB0_479
	ds_write2st64_b32 v123, v8, v9 offset0:98 offset1:102
	ds_write2st64_b32 v123, v10, v11 offset0:106 offset1:110
.LBB0_479:
	s_or_b64 exec, exec, s[6:7]
	s_waitcnt lgkmcnt(0)
	s_cmp_eq_u64 s[16:17], 0
	s_cselect_b32 s11, 1, 0
	s_lshl_b32 s82, s10, 1
	s_add_i32 s11, s11, s82
	s_lshl_b32 s82, s11, 10
	s_add_u32 s14, s14, s82
	s_addc_u32 s15, s15, 0
	s_add_u32 s28, s28, s82
	s_addc_u32 s29, s29, 0
	s_mul_i32 s82, s11, 0xc00
	s_add_u32 s12, s12, s82
	s_addc_u32 s13, s13, 0
	s_lshl_b32 s82, s10, 10
	s_add_u32 s76, s76, s82
	s_addc_u32 s77, s77, 0
	s_add_u32 s78, s78, s82
	s_addc_u32 s79, s79, 0
	s_add_u32 s80, s80, s82
	s_addc_u32 s81, s81, 0
	v_readfirstlane_b32 s11, v160
	s_lshr_b32 s11, s11, 6
	s_mov_b64 s[82:83], s[12:13]
	s_cmp_eq_u32 s11, 1
	s_cbranch_scc0 .Lpps_1
	s_add_u32 s82, s12, 0x400
	s_addc_u32 s83, s13, 0
.Lpps_1:
	s_cmp_eq_u32 s11, 2
	s_cbranch_scc0 .Lpps_2
	s_add_u32 s82, s12, 0x800
	s_addc_u32 s83, s13, 0
.Lpps_2:
	s_cmp_eq_u32 s11, 3
	s_cselect_b32 s82, s76, s82
	s_cselect_b32 s83, s77, s83
	s_cmp_eq_u32 s11, 4
	s_cselect_b32 s82, s28, s82
	s_cselect_b32 s83, s29, s83
	s_cmp_eq_u32 s11, 5
	s_cselect_b32 s82, s14, s82
	s_cselect_b32 s83, s15, s83
	s_cmp_eq_u32 s11, 6
	s_cselect_b32 s82, s78, s82
	s_cselect_b32 s83, s79, s83
	s_cmp_eq_u32 s11, 7
	s_cselect_b32 s82, s80, s82
	s_cselect_b32 s83, s81, s83
	v_and_b32_e32 v251, 63, v160
	v_lshlrev_b32_e32 v251, 4, v251
	global_load_dwordx4 v[222:225], v251, s[82:83]
	v_lshl_add_u64 v[74:75], v[74:75], 0, v[62:63]
	global_load_dwordx4 v[0:3], v[74:75], off
	s_waitcnt vmcnt(0)
	v_mfma_f32_32x32x16_bf16 v[0:15], v[28:31], v[0:3], 0
	global_load_dwordx4 v[28:31], v[74:75], off offset:32
	s_waitcnt vmcnt(0)
	v_mfma_f32_32x32x16_bf16 v[0:15], v[24:27], v[28:31], v[0:15]
	global_load_dwordx4 v[24:27], v[74:75], off offset:64
	s_waitcnt vmcnt(0)
	v_mfma_f32_32x32x16_bf16 v[0:15], v[20:23], v[24:27], v[0:15]
	global_load_dwordx4 v[20:23], v[74:75], off offset:96
	s_waitcnt vmcnt(0)
	v_mfma_f32_32x32x16_bf16 v[0:15], v[16:19], v[20:23], v[0:15]
	s_nop 11
	ds_write2st64_b32 v124, v0, v1 offset0:34 offset1:38
	ds_write2st64_b32 v124, v2, v3 offset0:42 offset1:46
	ds_write2st64_b32 v124, v4, v5 offset0:66 offset1:70
	ds_write2st64_b32 v124, v6, v7 offset0:74 offset1:78
	s_and_saveexec_b64 s[6:7], s[38:39]
	s_cbranch_execz .LBB0_481
	ds_write2st64_b32 v125, v8, v9 offset0:98 offset1:102
	ds_write2st64_b32 v125, v10, v11 offset0:106 offset1:110

.LBB0_485:
	s_or_b64 exec, exec, s[6:7]
	v_lshl_add_u32 v0, s0, 8, v32
	v_readlane_b32 s60, v253, 46
	v_ashrrev_i32_e32 v1, 31, v0
	v_readlane_b32 s61, v253, 47
	v_readlane_b32 s62, v253, 48
	v_readlane_b32 s63, v253, 49
	v_readlane_b32 s64, v253, 50
	v_readlane_b32 s65, v253, 51
	v_readlane_b32 s66, v253, 52
	v_readlane_b32 s67, v253, 53
	v_lshlrev_b64 v[2:3], 2, v[0:1]
	v_readlane_b32 s52, v253, 62
	v_lshl_add_u32 v0, s0, 9, v0
	v_readlane_b32 s70, v253, 56
	v_readlane_b32 s71, v253, 57
	v_readlane_b32 s74, v253, 60
	v_readlane_b32 s75, v253, 61
	v_readlane_b32 s54, v254, 0
	v_readlane_b32 s55, v254, 1
	v_ashrrev_i32_e32 v1, 31, v0
	v_lshl_add_u64 v[4:5], s[74:75], 0, v[2:3]
	v_lshl_add_u64 v[2:3], s[54:55], 0, v[2:3]
	s_mul_i32 s1, s0, 0x300
	v_lshl_add_u64 v[0:1], v[0:1], 2, s[70:71]
	v_readfirstlane_b32 s82, v160
	s_lshr_b32 s82, s82, 6
	s_lshl_b32 s82, s82, 10
	s_add_i32 s82, s82, 0xd000
	v_add_u32_e32 v249, s82, v251
	ds_write_b128 v249, v[222:225]
	s_waitcnt lgkmcnt(0)
	s_barrier
	s_xor_b64 s[18:19], s[16:17], -1
	v_readlane_b32 s22, v254, 34
	v_readlane_b32 s72, v254, 43
	v_readlane_b32 s73, v254, 44
	v_readlane_b32 s92, v254, 49
	v_readfirstlane_b32 s0, v160
	s_lshr_b32 s0, s0, 6
	s_and_b32 s0, s0, 3
	s_mul_i32 s53, s51, 20
	s_add_i32 s53, s53, s0
	s_lshl_b32 s0, s0, 10
	s_add_i32 s92, s92, s0
	v_and_b32_e32 v250, 63, v160
	v_lshlrev_b32_e32 v251, 4, v250
	v_lshlrev_b32_e32 v250, 3, v250
	v_add_u32_e32 v31, s92, v251
	s_add_u32 s28, s72, 0x664a000
	s_addc_u32 s29, s73, 0
	s_add_u32 s34, s72, 0xaeca000
	s_addc_u32 s35, s73, 0
	s_add_u32 s42, s72, 0x13aca000
	s_addc_u32 s43, s73, 0
	s_waitcnt lgkmcnt(0)
	s_cmp_eq_u64 s[16:17], 0
	s_cbranch_scc1 .Lprep_tok_d1
	ds_read_b128 v[210:213], v251 offset:53248
	ds_read_b128 v[214:217], v251 offset:54272
	ds_read_b128 v[218:221], v251 offset:55296
	ds_read_b128 v[198:201], v251 offset:56320
	ds_read_b128 v[194:197], v251 offset:57344
	ds_read_b128 v[190:193], v251 offset:58368
	ds_read_b128 v[202:205], v251 offset:59392
	ds_read_b128 v[206:209], v251 offset:60416
	s_add_i32 s56, s53, 0
	s_cmpk_lt_i32 s56, 0x2000
	s_movk_i32 s0, 0x3ff
	s_cselect_b32 s0, 0xff, s0
	s_and_b32 s1, s56, s0
	s_cmp_lg_u32 s1, 0
	s_cselect_b32 s59, 1.0, 0
	s_cselect_b32 s1, -1, 0
	s_add_i32 s1, s56, s1
	s_mul_i32 s0, s56, 0x1d00
	s_add_u32 s76, s28, s0
	s_addc_u32 s77, s29, 0
	s_mul_i32 s0, s1, 0x1d00
	s_add_u32 s78, s28, s0
	s_addc_u32 s79, s29, 0
	global_load_dwordx2 v[222:223], v250, s[76:77] offset:0
	global_load_dwordx2 v[224:225], v250, s[76:77] offset:512
	global_load_dwordx2 v[226:227], v250, s[76:77] offset:1024
	global_load_dwordx2 v[228:229], v250, s[78:79] offset:0
	global_load_dwordx2 v[230:231], v250, s[78:79] offset:512
	global_load_dwordx2 v[232:233], v250, s[78:79] offset:1024
	s_add_i32 s57, s53, 4
	s_cmpk_lt_i32 s57, 0x2000
	s_movk_i32 s0, 0x3ff
	s_cselect_b32 s0, 0xff, s0
	s_and_b32 s1, s57, s0
	s_cmp_lg_u32 s1, 0
	s_cselect_b32 s60, 1.0, 0
	s_cselect_b32 s1, -1, 0
	s_add_i32 s1, s57, s1
	s_mul_i32 s0, s57, 0x1d00
	s_add_u32 s80, s28, s0
	s_addc_u32 s81, s29, 0
	s_mul_i32 s0, s1, 0x1d00
	s_add_u32 s82, s28, s0
	s_addc_u32 s83, s29, 0
	global_load_dwordx2 v[236:237], v250, s[80:81] offset:0
	global_load_dwordx2 v[238:239], v250, s[80:81] offset:512
	global_load_dwordx2 v[240:241], v250, s[80:81] offset:1024
	global_load_dwordx2 v[242:243], v250, s[82:83] offset:0
	global_load_dwordx2 v[244:245], v250, s[82:83] offset:512
	global_load_dwordx2 v[246:247], v250, s[82:83] offset:1024
	s_add_i32 s58, s53, 8
	s_cmpk_lt_i32 s58, 0x2000
	s_movk_i32 s0, 0x3ff
	s_cselect_b32 s0, 0xff, s0
	s_and_b32 s1, s58, s0
	s_cmp_lg_u32 s1, 0
	s_cselect_b32 s61, 1.0, 0
	s_cselect_b32 s1, -1, 0
	s_add_i32 s1, s58, s1
	s_mul_i32 s0, s58, 0x1d00
	s_add_u32 s84, s28, s0
	s_addc_u32 s85, s29, 0
	s_mul_i32 s0, s1, 0x1d00
	s_add_u32 s96, s28, s0
	s_addc_u32 s97, s29, 0
	global_load_dwordx2 v[0:1], v250, s[84:85] offset:0
	global_load_dwordx2 v[2:3], v250, s[84:85] offset:512
	global_load_dwordx2 v[4:5], v250, s[84:85] offset:1024
	global_load_dwordx2 v[6:7], v250, s[96:97] offset:0
	global_load_dwordx2 v[8:9], v250, s[96:97] offset:512
	global_load_dwordx2 v[10:11], v250, s[96:97] offset:1024
	ds_read_b128 v[14:17], v31 offset:0
	ds_read_b128 v[18:21], v31 offset:20480
	ds_read_b128 v[22:25], v31 offset:4096
	ds_read_b128 v[26:29], v31 offset:24576
	s_waitcnt lgkmcnt(4)
	s_waitcnt vmcnt(12)
	v_lshlrev_b32_e32 v134, 16, v222
	v_and_b32_e32 v222, 0xffff0000, v222
	v_lshlrev_b32_e32 v135, 16, v223
	v_and_b32_e32 v223, 0xffff0000, v223
	v_lshlrev_b32_e32 v136, 16, v224
	v_and_b32_e32 v224, 0xffff0000, v224
	v_lshlrev_b32_e32 v137, 16, v225
	v_and_b32_e32 v225, 0xffff0000, v225
	v_lshlrev_b32_e32 v138, 16, v226
	v_and_b32_e32 v226, 0xffff0000, v226
	v_lshlrev_b32_e32 v139, 16, v227
	v_and_b32_e32 v227, 0xffff0000, v227
	v_lshlrev_b32_e32 v140, 16, v228
	v_and_b32_e32 v228, 0xffff0000, v228
	v_lshlrev_b32_e32 v141, 16, v229
	v_and_b32_e32 v229, 0xffff0000, v229
	v_lshlrev_b32_e32 v142, 16, v230
	v_and_b32_e32 v230, 0xffff0000, v230
	v_lshlrev_b32_e32 v143, 16, v231
	v_and_b32_e32 v231, 0xffff0000, v231
	v_lshlrev_b32_e32 v144, 16, v232
	v_and_b32_e32 v232, 0xffff0000, v232
	v_lshlrev_b32_e32 v145, 16, v233
	v_and_b32_e32 v233, 0xffff0000, v233
	v_fma_f32 v140, s59, v140, -v134
	v_fma_f32 v228, s59, v228, -v222
	v_fma_f32 v141, s59, v141, -v135
	v_fma_f32 v229, s59, v229, -v223
	v_fmac_f32_e32 v134, v210, v140
	v_fmac_f32_e32 v222, v211, v228
	v_fmac_f32_e32 v135, v212, v141
	v_fmac_f32_e32 v223, v213, v229
	v_fma_f32 v142, s59, v142, -v136
	v_fma_f32 v230, s59, v230, -v224
	v_fma_f32 v143, s59, v143, -v137
	v_fma_f32 v231, s59, v231, -v225
	v_fmac_f32_e32 v136, v214, v142
	v_fmac_f32_e32 v224, v215, v230
	v_fmac_f32_e32 v137, v216, v143
	v_fmac_f32_e32 v225, v217, v231
	v_fma_f32 v144, s59, v144, -v138
	v_fma_f32 v232, s59, v232, -v226
	v_fma_f32 v145, s59, v145, -v139
	v_fma_f32 v233, s59, v233, -v227
	v_fmac_f32_e32 v138, v218, v144
	v_fmac_f32_e32 v226, v219, v232
	v_fmac_f32_e32 v139, v220, v145
	v_fmac_f32_e32 v227, v221, v233
	v_mul_f32_e32 v148, v198, v136
	v_mul_f32_e32 v149, v199, v224
	v_mul_f32_e32 v150, v200, v137
	v_mul_f32_e32 v151, v201, v225
	v_mul_f32_e32 v176, v148, v148
	v_fmac_f32_e32 v176, v149, v149
	v_fmac_f32_e32 v176, v150, v150
	v_fmac_f32_e32 v176, v151, v151
	s_waitcnt lgkmcnt(2)
	v_add_f32_e32 v18, v194, v18
	v_add_f32_e32 v19, v195, v19
	v_add_f32_e32 v20, v196, v20
	v_add_f32_e32 v21, v197, v21
	v_add_f32_dpp v176, v176, v176 quad_perm:[1,0,3,2] row_mask:0xf bank_mask:0xf bound_ctrl:1
	v_mul_f32_e32 v18, 0xbfb8aa3b, v18
	v_mul_f32_e32 v19, 0xbfb8aa3b, v19
	v_mul_f32_e32 v20, 0xbfb8aa3b, v20
	v_mul_f32_e32 v21, 0xbfb8aa3b, v21
	v_add_f32_dpp v176, v176, v176 quad_perm:[2,3,0,1] row_mask:0xf bank_mask:0xf bound_ctrl:1
	v_exp_f32_e32 v18, v18
	v_exp_f32_e32 v19, v19
	v_exp_f32_e32 v20, v20
	v_exp_f32_e32 v21, v21
	v_add_f32_dpp v176, v176, v176 row_half_mirror row_mask:0xf bank_mask:0xf bound_ctrl:1
	v_add_f32_e32 v18, 1.0, v18
	v_add_f32_e32 v19, 1.0, v19
	v_add_f32_e32 v20, 1.0, v20
	v_add_f32_e32 v21, 1.0, v21
	v_add_f32_dpp v176, v176, v176 row_mirror row_mask:0xf bank_mask:0xf bound_ctrl:1
	v_rcp_f32_e32 v18, v18
	v_rcp_f32_e32 v19, v19
	v_rcp_f32_e32 v20, v20
	v_rcp_f32_e32 v21, v21
	v_sqrt_f32_e32 v176, v176
	v_add_f32_e32 v14, v190, v14
	v_add_f32_e32 v15, v191, v15
	v_add_f32_e32 v16, v192, v16
	v_add_f32_e32 v17, v193, v17
	v_max_f32_e32 v176, 0x2b8cbccc, v176
	v_mul_f32_e32 v14, 0xbfb8aa3b, v14
	v_mul_f32_e32 v15, 0xbfb8aa3b, v15
	v_mul_f32_e32 v16, 0xbfb8aa3b, v16
	v_mul_f32_e32 v17, 0xbfb8aa3b, v17
	v_rcp_f32_e32 v178, v176
	v_exp_f32_e32 v14, v14
	v_exp_f32_e32 v15, v15
	v_exp_f32_e32 v16, v16
	v_exp_f32_e32 v17, v17
	v_add_f32_e32 v14, 1.0, v14
	v_add_f32_e32 v15, 1.0, v15
	v_add_f32_e32 v16, 1.0, v16
	v_add_f32_e32 v17, 1.0, v17
	v_rcp_f32_e32 v14, v14
	v_rcp_f32_e32 v15, v15
	v_rcp_f32_e32 v16, v16
	v_rcp_f32_e32 v17, v17
	v_mul_f32_e32 v14, 0xbf1b4598, v14
	v_mul_f32_e32 v15, 0xbf1b4598, v15
	v_mul_f32_e32 v16, 0xbf1b4598, v16
	v_mul_f32_e32 v17, 0xbf1b4598, v17
	v_mul_f32_e32 v14, 0x3fb8aa3b, v14
	v_mul_f32_e32 v15, 0x3fb8aa3b, v15
	v_mul_f32_e32 v16, 0x3fb8aa3b, v16
	v_mul_f32_e32 v17, 0x3fb8aa3b, v17
	v_exp_f32_e32 v14, v14
	v_exp_f32_e32 v15, v15
	v_exp_f32_e32 v16, v16
	v_exp_f32_e32 v17, v17
	v_add_f32_e32 v152, -1.0, v18
	v_add_f32_e32 v153, -1.0, v19
	v_add_f32_e32 v154, -1.0, v20
	v_add_f32_e32 v155, -1.0, v21
	v_fma_f32 v152, v202, v152, 1.0
	v_fma_f32 v153, v203, v153, 1.0
	v_fma_f32 v154, v204, v154, 1.0
	v_fma_f32 v155, v205, v155, 1.0
	v_mul_f32_e32 v152, v136, v152
	v_mul_f32_e32 v153, v224, v153
	v_mul_f32_e32 v154, v137, v154
	v_mul_f32_e32 v155, v225, v155
	v_mul_f32_e32 v156, v134, v152
	v_mul_f32_e32 v157, v222, v153
	v_mul_f32_e32 v158, v135, v154
	v_mul_f32_e32 v159, v223, v155
	v_mul_f32_e32 v177, v206, v156
	v_fmac_f32_e32 v177, v207, v157
	v_fmac_f32_e32 v177, v208, v158
	v_fmac_f32_e32 v177, v209, v159
	v_mul_f32_e32 v148, v148, v178
	v_mul_f32_e32 v149, v149, v178
	v_add_f32_dpp v177, v177, v177 quad_perm:[1,0,3,2] row_mask:0xf bank_mask:0xf bound_ctrl:1
	v_mul_f32_e32 v150, v150, v178
	v_mul_f32_e32 v151, v151, v178
	v_add_f32_dpp v177, v177, v177 quad_perm:[2,3,0,1] row_mask:0xf bank_mask:0xf bound_ctrl:1
	v_mul_f32_e32 v18, v18, v148
	v_mul_f32_e32 v19, v19, v149
	v_add_f32_dpp v177, v177, v177 row_half_mirror row_mask:0xf bank_mask:0xf bound_ctrl:1
	v_mul_f32_e32 v20, v20, v150
	v_mul_f32_e32 v21, v21, v151
	v_add_f32_dpp v177, v177, v177 row_mirror row_mask:0xf bank_mask:0xf bound_ctrl:1
	s_lshl_b32 s0, s56, 9
	s_add_u32 s62, s34, s0
	s_addc_u32 s63, s35, 0
	v_mul_f32_e32 v156, v138, v177
	v_mul_f32_e32 v157, v226, v177
	v_mul_f32_e32 v158, v139, v177
	v_mul_f32_e32 v159, v227, v177
	v_cvt_pk_bf16_f32 v72, v134, v222
	v_cvt_pk_bf16_f32 v73, v135, v223
	global_store_dwordx2 v250, v[72:73], s[62:63]
	v_cvt_pk_bf16_f32 v74, v14, v15
	v_cvt_pk_bf16_f32 v75, v16, v17
	s_add_u32 s0, s62, 0x500000
	s_addc_u32 s1, s63, 0
	global_store_dwordx2 v250, v[74:75], s[0:1]
	v_cvt_pk_bf16_f32 v180, v152, v153
	v_cvt_pk_bf16_f32 v181, v154, v155
	s_add_u32 s0, s62, 0xa00000
	s_addc_u32 s1, s63, 0
	global_store_dwordx2 v250, v[180:181], s[0:1]
	v_cvt_pk_bf16_f32 v72, v138, v226
	v_cvt_pk_bf16_f32 v73, v139, v227
	s_add_u32 s0, s62, 0xf00000
	s_addc_u32 s1, s63, 0
	global_store_dwordx2 v250, v[72:73], s[0:1]
	v_cvt_pk_bf16_f32 v74, v148, v149
	v_cvt_pk_bf16_f32 v75, v150, v151
	s_add_u32 s0, s62, 0x1400000
	s_addc_u32 s1, s63, 0
	global_store_dwordx2 v250, v[74:75], s[0:1]
	v_cvt_pk_bf16_f32 v180, v18, v19
	v_cvt_pk_bf16_f32 v181, v20, v21
	s_add_u32 s0, s62, 0x1900000
	s_addc_u32 s1, s63, 0
	global_store_dwordx2 v250, v[180:181], s[0:1]
	v_cvt_pk_bf16_f32 v72, v156, v157
	v_cvt_pk_bf16_f32 v73, v158, v159
	s_lshl_b32 s0, s56, 9
	s_add_u32 s0, s42, s0
	s_addc_u32 s1, s43, 0
	global_store_dwordx2 v250, v[72:73], s[0:1]
	s_add_i32 s56, s53, 12
	s_cmpk_lt_i32 s56, 0x2000
	s_movk_i32 s0, 0x3ff
	s_cselect_b32 s0, 0xff, s0
	s_and_b32 s1, s56, s0
	s_cmp_lg_u32 s1, 0
	s_cselect_b32 s59, 1.0, 0
	s_cselect_b32 s1, -1, 0
	s_add_i32 s1, s56, s1
	s_mul_i32 s0, s56, 0x1d00
	s_add_u32 s76, s28, s0
	s_addc_u32 s77, s29, 0
	s_mul_i32 s0, s1, 0x1d00
	s_add_u32 s78, s28, s0
	s_addc_u32 s79, s29, 0
	global_load_dwordx2 v[222:223], v250, s[76:77] offset:0
	global_load_dwordx2 v[224:225], v250, s[76:77] offset:512
	global_load_dwordx2 v[226:227], v250, s[76:77] offset:1024
	global_load_dwordx2 v[228:229], v250, s[78:79] offset:0
	global_load_dwordx2 v[230:231], v250, s[78:79] offset:512
	global_load_dwordx2 v[232:233], v250, s[78:79] offset:1024
	ds_read_b128 v[14:17], v31 offset:8192
	ds_read_b128 v[18:21], v31 offset:28672
	s_waitcnt vmcnt(19)
	v_lshlrev_b32_e32 v134, 16, v236
	v_and_b32_e32 v236, 0xffff0000, v236
	v_lshlrev_b32_e32 v135, 16, v237
	v_and_b32_e32 v237, 0xffff0000, v237
	v_lshlrev_b32_e32 v136, 16, v238
	v_and_b32_e32 v238, 0xffff0000, v238
	v_lshlrev_b32_e32 v137, 16, v239
	v_and_b32_e32 v239, 0xffff0000, v239
	v_lshlrev_b32_e32 v138, 16, v240
	v_and_b32_e32 v240, 0xffff0000, v240
	v_lshlrev_b32_e32 v139, 16, v241
	v_and_b32_e32 v241, 0xffff0000, v241
	v_lshlrev_b32_e32 v140, 16, v242
	v_and_b32_e32 v242, 0xffff0000, v242
	v_lshlrev_b32_e32 v141, 16, v243
	v_and_b32_e32 v243, 0xffff0000, v243
	v_lshlrev_b32_e32 v142, 16, v244
	v_and_b32_e32 v244, 0xffff0000, v244
	v_lshlrev_b32_e32 v143, 16, v245
	v_and_b32_e32 v245, 0xffff0000, v245
	v_lshlrev_b32_e32 v144, 16, v246
	v_and_b32_e32 v246, 0xffff0000, v246
	v_lshlrev_b32_e32 v145, 16, v247
	v_and_b32_e32 v247, 0xffff0000, v247
	v_fma_f32 v140, s60, v140, -v134
	v_fma_f32 v242, s60, v242, -v236
	v_fma_f32 v141, s60, v141, -v135
	v_fma_f32 v243, s60, v243, -v237
	v_fmac_f32_e32 v134, v210, v140
	v_fmac_f32_e32 v236, v211, v242
	v_fmac_f32_e32 v135, v212, v141
	v_fmac_f32_e32 v237, v213, v243
	v_fma_f32 v142, s60, v142, -v136
	v_fma_f32 v244, s60, v244, -v238
	v_fma_f32 v143, s60, v143, -v137
	v_fma_f32 v245, s60, v245, -v239
	v_fmac_f32_e32 v136, v214, v142
	v_fmac_f32_e32 v238, v215, v244
	v_fmac_f32_e32 v137, v216, v143
	v_fmac_f32_e32 v239, v217, v245
	v_fma_f32 v144, s60, v144, -v138
	v_fma_f32 v246, s60, v246, -v240
	v_fma_f32 v145, s60, v145, -v139
	v_fma_f32 v247, s60, v247, -v241
	v_fmac_f32_e32 v138, v218, v144
	v_fmac_f32_e32 v240, v219, v246
	v_fmac_f32_e32 v139, v220, v145
	v_fmac_f32_e32 v241, v221, v247
	v_mul_f32_e32 v148, v198, v136
	v_mul_f32_e32 v149, v199, v238
	v_mul_f32_e32 v150, v200, v137
	v_mul_f32_e32 v151, v201, v239
	v_mul_f32_e32 v176, v148, v148
	v_fmac_f32_e32 v176, v149, v149
	v_fmac_f32_e32 v176, v150, v150
	v_fmac_f32_e32 v176, v151, v151
	s_waitcnt lgkmcnt(2)
	v_add_f32_e32 v26, v194, v26
	v_add_f32_e32 v27, v195, v27
	v_add_f32_e32 v28, v196, v28
	v_add_f32_e32 v29, v197, v29
	v_add_f32_dpp v176, v176, v176 quad_perm:[1,0,3,2] row_mask:0xf bank_mask:0xf bound_ctrl:1
	v_mul_f32_e32 v26, 0xbfb8aa3b, v26
	v_mul_f32_e32 v27, 0xbfb8aa3b, v27
	v_mul_f32_e32 v28, 0xbfb8aa3b, v28
	v_mul_f32_e32 v29, 0xbfb8aa3b, v29
	v_add_f32_dpp v176, v176, v176 quad_perm:[2,3,0,1] row_mask:0xf bank_mask:0xf bound_ctrl:1
	v_exp_f32_e32 v26, v26
	v_exp_f32_e32 v27, v27
	v_exp_f32_e32 v28, v28
	v_exp_f32_e32 v29, v29
	v_add_f32_dpp v176, v176, v176 row_half_mirror row_mask:0xf bank_mask:0xf bound_ctrl:1
	v_add_f32_e32 v26, 1.0, v26
	v_add_f32_e32 v27, 1.0, v27
	v_add_f32_e32 v28, 1.0, v28
	v_add_f32_e32 v29, 1.0, v29
	v_add_f32_dpp v176, v176, v176 row_mirror row_mask:0xf bank_mask:0xf bound_ctrl:1
	v_rcp_f32_e32 v26, v26
	v_rcp_f32_e32 v27, v27
	v_rcp_f32_e32 v28, v28
	v_rcp_f32_e32 v29, v29
	v_sqrt_f32_e32 v176, v176
	v_add_f32_e32 v22, v190, v22
	v_add_f32_e32 v23, v191, v23
	v_add_f32_e32 v24, v192, v24
	v_add_f32_e32 v25, v193, v25
	v_max_f32_e32 v176, 0x2b8cbccc, v176
	v_mul_f32_e32 v22, 0xbfb8aa3b, v22
	v_mul_f32_e32 v23, 0xbfb8aa3b, v23
	v_mul_f32_e32 v24, 0xbfb8aa3b, v24
	v_mul_f32_e32 v25, 0xbfb8aa3b, v25
	v_rcp_f32_e32 v178, v176
	v_exp_f32_e32 v22, v22
	v_exp_f32_e32 v23, v23
	v_exp_f32_e32 v24, v24
	v_exp_f32_e32 v25, v25
	v_add_f32_e32 v22, 1.0, v22
	v_add_f32_e32 v23, 1.0, v23
	v_add_f32_e32 v24, 1.0, v24
	v_add_f32_e32 v25, 1.0, v25
	v_rcp_f32_e32 v22, v22
	v_rcp_f32_e32 v23, v23
	v_rcp_f32_e32 v24, v24
	v_rcp_f32_e32 v25, v25
	v_mul_f32_e32 v22, 0xbf1b4598, v22
	v_mul_f32_e32 v23, 0xbf1b4598, v23
	v_mul_f32_e32 v24, 0xbf1b4598, v24
	v_mul_f32_e32 v25, 0xbf1b4598, v25
	v_mul_f32_e32 v22, 0x3fb8aa3b, v22
	v_mul_f32_e32 v23, 0x3fb8aa3b, v23
	v_mul_f32_e32 v24, 0x3fb8aa3b, v24
	v_mul_f32_e32 v25, 0x3fb8aa3b, v25
	v_exp_f32_e32 v22, v22
	v_exp_f32_e32 v23, v23
	v_exp_f32_e32 v24, v24
	v_exp_f32_e32 v25, v25
	v_add_f32_e32 v152, -1.0, v26
	v_add_f32_e32 v153, -1.0, v27
	v_add_f32_e32 v154, -1.0, v28
	v_add_f32_e32 v155, -1.0, v29
	v_fma_f32 v152, v202, v152, 1.0
	v_fma_f32 v153, v203, v153, 1.0
	v_fma_f32 v154, v204, v154, 1.0
	v_fma_f32 v155, v205, v155, 1.0
	v_mul_f32_e32 v152, v136, v152
	v_mul_f32_e32 v153, v238, v153
	v_mul_f32_e32 v154, v137, v154
	v_mul_f32_e32 v155, v239, v155
	v_mul_f32_e32 v156, v134, v152
	v_mul_f32_e32 v157, v236, v153
	v_mul_f32_e32 v158, v135, v154
	v_mul_f32_e32 v159, v237, v155
	v_mul_f32_e32 v177, v206, v156
	v_fmac_f32_e32 v177, v207, v157
	v_fmac_f32_e32 v177, v208, v158
	v_fmac_f32_e32 v177, v209, v159
	v_mul_f32_e32 v148, v148, v178
	v_mul_f32_e32 v149, v149, v178
	v_add_f32_dpp v177, v177, v177 quad_perm:[1,0,3,2] row_mask:0xf bank_mask:0xf bound_ctrl:1
	v_mul_f32_e32 v150, v150, v178
	v_mul_f32_e32 v151, v151, v178
	v_add_f32_dpp v177, v177, v177 quad_perm:[2,3,0,1] row_mask:0xf bank_mask:0xf bound_ctrl:1
	v_mul_f32_e32 v26, v26, v148
	v_mul_f32_e32 v27, v27, v149
	v_add_f32_dpp v177, v177, v177 row_half_mirror row_mask:0xf bank_mask:0xf bound_ctrl:1
	v_mul_f32_e32 v28, v28, v150
	v_mul_f32_e32 v29, v29, v151
	v_add_f32_dpp v177, v177, v177 row_mirror row_mask:0xf bank_mask:0xf bound_ctrl:1
	s_lshl_b32 s0, s57, 9
	s_add_u32 s62, s34, s0
	s_addc_u32 s63, s35, 0
	v_mul_f32_e32 v156, v138, v177
	v_mul_f32_e32 v157, v240, v177
	v_mul_f32_e32 v158, v139, v177
	v_mul_f32_e32 v159, v241, v177
	v_cvt_pk_bf16_f32 v72, v134, v236
	v_cvt_pk_bf16_f32 v73, v135, v237
	global_store_dwordx2 v250, v[72:73], s[62:63]
	v_cvt_pk_bf16_f32 v74, v22, v23
	v_cvt_pk_bf16_f32 v75, v24, v25
	s_add_u32 s0, s62, 0x500000
	s_addc_u32 s1, s63, 0
	global_store_dwordx2 v250, v[74:75], s[0:1]
	v_cvt_pk_bf16_f32 v180, v152, v153
	v_cvt_pk_bf16_f32 v181, v154, v155
	s_add_u32 s0, s62, 0xa00000
	s_addc_u32 s1, s63, 0
	global_store_dwordx2 v250, v[180:181], s[0:1]
	v_cvt_pk_bf16_f32 v72, v138, v240
	v_cvt_pk_bf16_f32 v73, v139, v241
	s_add_u32 s0, s62, 0xf00000
	s_addc_u32 s1, s63, 0
	global_store_dwordx2 v250, v[72:73], s[0:1]
	v_cvt_pk_bf16_f32 v74, v148, v149
	v_cvt_pk_bf16_f32 v75, v150, v151
	s_add_u32 s0, s62, 0x1400000
	s_addc_u32 s1, s63, 0
	global_store_dwordx2 v250, v[74:75], s[0:1]
	v_cvt_pk_bf16_f32 v180, v26, v27
	v_cvt_pk_bf16_f32 v181, v28, v29
	s_add_u32 s0, s62, 0x1900000
	s_addc_u32 s1, s63, 0
	global_store_dwordx2 v250, v[180:181], s[0:1]
	v_cvt_pk_bf16_f32 v72, v156, v157
	v_cvt_pk_bf16_f32 v73, v158, v159
	s_lshl_b32 s0, s57, 9
	s_add_u32 s0, s42, s0
	s_addc_u32 s1, s43, 0
	global_store_dwordx2 v250, v[72:73], s[0:1]
	s_add_i32 s57, s53, 16
	s_cmpk_lt_i32 s57, 0x2000
	s_movk_i32 s0, 0x3ff
	s_cselect_b32 s0, 0xff, s0
	s_and_b32 s1, s57, s0
	s_cmp_lg_u32 s1, 0
	s_cselect_b32 s60, 1.0, 0
	s_cselect_b32 s1, -1, 0
	s_add_i32 s1, s57, s1
	s_mul_i32 s0, s57, 0x1d00
	s_add_u32 s80, s28, s0
	s_addc_u32 s81, s29, 0
	s_mul_i32 s0, s1, 0x1d00
	s_add_u32 s82, s28, s0
	s_addc_u32 s83, s29, 0
	global_load_dwordx2 v[236:237], v250, s[80:81] offset:0
	global_load_dwordx2 v[238:239], v250, s[80:81] offset:512
	global_load_dwordx2 v[240:241], v250, s[80:81] offset:1024
	global_load_dwordx2 v[242:243], v250, s[82:83] offset:0
	global_load_dwordx2 v[244:245], v250, s[82:83] offset:512
	global_load_dwordx2 v[246:247], v250, s[82:83] offset:1024
	ds_read_b128 v[22:25], v31 offset:12288
	ds_read_b128 v[26:29], v31 offset:32768
	s_waitcnt vmcnt(26)
	v_lshlrev_b32_e32 v134, 16, v0
	v_and_b32_e32 v0, 0xffff0000, v0
	v_lshlrev_b32_e32 v135, 16, v1
	v_and_b32_e32 v1, 0xffff0000, v1
	v_lshlrev_b32_e32 v136, 16, v2
	v_and_b32_e32 v2, 0xffff0000, v2
	v_lshlrev_b32_e32 v137, 16, v3
	v_and_b32_e32 v3, 0xffff0000, v3
	v_lshlrev_b32_e32 v138, 16, v4
	v_and_b32_e32 v4, 0xffff0000, v4
	v_lshlrev_b32_e32 v139, 16, v5
	v_and_b32_e32 v5, 0xffff0000, v5
	v_lshlrev_b32_e32 v140, 16, v6
	v_and_b32_e32 v6, 0xffff0000, v6
	v_lshlrev_b32_e32 v141, 16, v7
	v_and_b32_e32 v7, 0xffff0000, v7
	v_lshlrev_b32_e32 v142, 16, v8
	v_and_b32_e32 v8, 0xffff0000, v8
	v_lshlrev_b32_e32 v143, 16, v9
	v_and_b32_e32 v9, 0xffff0000, v9
	v_lshlrev_b32_e32 v144, 16, v10
	v_and_b32_e32 v10, 0xffff0000, v10
	v_lshlrev_b32_e32 v145, 16, v11
	v_and_b32_e32 v11, 0xffff0000, v11
	v_fma_f32 v140, s61, v140, -v134
	v_fma_f32 v6, s61, v6, -v0
	v_fma_f32 v141, s61, v141, -v135
	v_fma_f32 v7, s61, v7, -v1
	v_fmac_f32_e32 v134, v210, v140
	v_fmac_f32_e32 v0, v211, v6
	v_fmac_f32_e32 v135, v212, v141
	v_fmac_f32_e32 v1, v213, v7
	v_fma_f32 v142, s61, v142, -v136
	v_fma_f32 v8, s61, v8, -v2
	v_fma_f32 v143, s61, v143, -v137
	v_fma_f32 v9, s61, v9, -v3
	v_fmac_f32_e32 v136, v214, v142
	v_fmac_f32_e32 v2, v215, v8
	v_fmac_f32_e32 v137, v216, v143
	v_fmac_f32_e32 v3, v217, v9
	v_fma_f32 v144, s61, v144, -v138
	v_fma_f32 v10, s61, v10, -v4
	v_fma_f32 v145, s61, v145, -v139
	v_fma_f32 v11, s61, v11, -v5
	v_fmac_f32_e32 v138, v218, v144
	v_fmac_f32_e32 v4, v219, v10
	v_fmac_f32_e32 v139, v220, v145
	v_fmac_f32_e32 v5, v221, v11
	v_mul_f32_e32 v148, v198, v136
	v_mul_f32_e32 v149, v199, v2
	v_mul_f32_e32 v150, v200, v137
	v_mul_f32_e32 v151, v201, v3
	v_mul_f32_e32 v176, v148, v148
	v_fmac_f32_e32 v176, v149, v149
	v_fmac_f32_e32 v176, v150, v150
	v_fmac_f32_e32 v176, v151, v151
	s_waitcnt lgkmcnt(2)
	v_add_f32_e32 v18, v194, v18
	v_add_f32_e32 v19, v195, v19
	v_add_f32_e32 v20, v196, v20
	v_add_f32_e32 v21, v197, v21
	v_add_f32_dpp v176, v176, v176 quad_perm:[1,0,3,2] row_mask:0xf bank_mask:0xf bound_ctrl:1
	v_mul_f32_e32 v18, 0xbfb8aa3b, v18
	v_mul_f32_e32 v19, 0xbfb8aa3b, v19
	v_mul_f32_e32 v20, 0xbfb8aa3b, v20
	v_mul_f32_e32 v21, 0xbfb8aa3b, v21
	v_add_f32_dpp v176, v176, v176 quad_perm:[2,3,0,1] row_mask:0xf bank_mask:0xf bound_ctrl:1
	v_exp_f32_e32 v18, v18
	v_exp_f32_e32 v19, v19
	v_exp_f32_e32 v20, v20
	v_exp_f32_e32 v21, v21
	v_add_f32_dpp v176, v176, v176 row_half_mirror row_mask:0xf bank_mask:0xf bound_ctrl:1
	v_add_f32_e32 v18, 1.0, v18
	v_add_f32_e32 v19, 1.0, v19
	v_add_f32_e32 v20, 1.0, v20
	v_add_f32_e32 v21, 1.0, v21
	v_add_f32_dpp v176, v176, v176 row_mirror row_mask:0xf bank_mask:0xf bound_ctrl:1
	v_rcp_f32_e32 v18, v18
	v_rcp_f32_e32 v19, v19
	v_rcp_f32_e32 v20, v20
	v_rcp_f32_e32 v21, v21
	v_sqrt_f32_e32 v176, v176
	v_add_f32_e32 v14, v190, v14
	v_add_f32_e32 v15, v191, v15
	v_add_f32_e32 v16, v192, v16
	v_add_f32_e32 v17, v193, v17
	v_max_f32_e32 v176, 0x2b8cbccc, v176
	v_mul_f32_e32 v14, 0xbfb8aa3b, v14
	v_mul_f32_e32 v15, 0xbfb8aa3b, v15
	v_mul_f32_e32 v16, 0xbfb8aa3b, v16
	v_mul_f32_e32 v17, 0xbfb8aa3b, v17
	v_rcp_f32_e32 v178, v176
	v_exp_f32_e32 v14, v14
	v_exp_f32_e32 v15, v15
	v_exp_f32_e32 v16, v16
	v_exp_f32_e32 v17, v17
	v_add_f32_e32 v14, 1.0, v14
	v_add_f32_e32 v15, 1.0, v15
	v_add_f32_e32 v16, 1.0, v16
	v_add_f32_e32 v17, 1.0, v17
	v_rcp_f32_e32 v14, v14
	v_rcp_f32_e32 v15, v15
	v_rcp_f32_e32 v16, v16
	v_rcp_f32_e32 v17, v17
	v_mul_f32_e32 v14, 0xbf1b4598, v14
	v_mul_f32_e32 v15, 0xbf1b4598, v15
	v_mul_f32_e32 v16, 0xbf1b4598, v16
	v_mul_f32_e32 v17, 0xbf1b4598, v17
	v_mul_f32_e32 v14, 0x3fb8aa3b, v14
	v_mul_f32_e32 v15, 0x3fb8aa3b, v15
	v_mul_f32_e32 v16, 0x3fb8aa3b, v16
	v_mul_f32_e32 v17, 0x3fb8aa3b, v17
	v_exp_f32_e32 v14, v14
	v_exp_f32_e32 v15, v15
	v_exp_f32_e32 v16, v16
	v_exp_f32_e32 v17, v17
	v_add_f32_e32 v152, -1.0, v18
	v_add_f32_e32 v153, -1.0, v19
	v_add_f32_e32 v154, -1.0, v20
	v_add_f32_e32 v155, -1.0, v21
	v_fma_f32 v152, v202, v152, 1.0
	v_fma_f32 v153, v203, v153, 1.0
	v_fma_f32 v154, v204, v154, 1.0
	v_fma_f32 v155, v205, v155, 1.0
	v_mul_f32_e32 v152, v136, v152
	v_mul_f32_e32 v153, v2, v153
	v_mul_f32_e32 v154, v137, v154
	v_mul_f32_e32 v155, v3, v155
	v_mul_f32_e32 v156, v134, v152
	v_mul_f32_e32 v157, v0, v153
	v_mul_f32_e32 v158, v135, v154
	v_mul_f32_e32 v159, v1, v155
	v_mul_f32_e32 v177, v206, v156
	v_fmac_f32_e32 v177, v207, v157
	v_fmac_f32_e32 v177, v208, v158
	v_fmac_f32_e32 v177, v209, v159
	v_mul_f32_e32 v148, v148, v178
	v_mul_f32_e32 v149, v149, v178
	v_add_f32_dpp v177, v177, v177 quad_perm:[1,0,3,2] row_mask:0xf bank_mask:0xf bound_ctrl:1
	v_mul_f32_e32 v150, v150, v178
	v_mul_f32_e32 v151, v151, v178
	v_add_f32_dpp v177, v177, v177 quad_perm:[2,3,0,1] row_mask:0xf bank_mask:0xf bound_ctrl:1
	v_mul_f32_e32 v18, v18, v148
	v_mul_f32_e32 v19, v19, v149
	v_add_f32_dpp v177, v177, v177 row_half_mirror row_mask:0xf bank_mask:0xf bound_ctrl:1
	v_mul_f32_e32 v20, v20, v150
	v_mul_f32_e32 v21, v21, v151
	v_add_f32_dpp v177, v177, v177 row_mirror row_mask:0xf bank_mask:0xf bound_ctrl:1
	s_lshl_b32 s0, s58, 9
	s_add_u32 s62, s34, s0
	s_addc_u32 s63, s35, 0
	v_mul_f32_e32 v156, v138, v177
	v_mul_f32_e32 v157, v4, v177
	v_mul_f32_e32 v158, v139, v177
	v_mul_f32_e32 v159, v5, v177
	v_cvt_pk_bf16_f32 v72, v134, v0
	v_cvt_pk_bf16_f32 v73, v135, v1
	global_store_dwordx2 v250, v[72:73], s[62:63]
	v_cvt_pk_bf16_f32 v74, v14, v15
	v_cvt_pk_bf16_f32 v75, v16, v17
	s_add_u32 s0, s62, 0x500000
	s_addc_u32 s1, s63, 0
	global_store_dwordx2 v250, v[74:75], s[0:1]
	v_cvt_pk_bf16_f32 v180, v152, v153
	v_cvt_pk_bf16_f32 v181, v154, v155
	s_add_u32 s0, s62, 0xa00000
	s_addc_u32 s1, s63, 0
	global_store_dwordx2 v250, v[180:181], s[0:1]
	v_cvt_pk_bf16_f32 v72, v138, v4
	v_cvt_pk_bf16_f32 v73, v139, v5
	s_add_u32 s0, s62, 0xf00000
	s_addc_u32 s1, s63, 0
	global_store_dwordx2 v250, v[72:73], s[0:1]
	v_cvt_pk_bf16_f32 v74, v148, v149
	v_cvt_pk_bf16_f32 v75, v150, v151
	s_add_u32 s0, s62, 0x1400000
	s_addc_u32 s1, s63, 0
	global_store_dwordx2 v250, v[74:75], s[0:1]
	v_cvt_pk_bf16_f32 v180, v18, v19
	v_cvt_pk_bf16_f32 v181, v20, v21
	s_add_u32 s0, s62, 0x1900000
	s_addc_u32 s1, s63, 0
	global_store_dwordx2 v250, v[180:181], s[0:1]
	v_cvt_pk_bf16_f32 v72, v156, v157
	v_cvt_pk_bf16_f32 v73, v158, v159
	s_lshl_b32 s0, s58, 9
	s_add_u32 s0, s42, s0
	s_addc_u32 s1, s43, 0
	global_store_dwordx2 v250, v[72:73], s[0:1]
	ds_read_b128 v[14:17], v31 offset:16384
	ds_read_b128 v[18:21], v31 offset:36864
	s_waitcnt vmcnt(20)
	v_lshlrev_b32_e32 v134, 16, v222
	v_and_b32_e32 v222, 0xffff0000, v222
	v_lshlrev_b32_e32 v135, 16, v223
	v_and_b32_e32 v223, 0xffff0000, v223
	v_lshlrev_b32_e32 v136, 16, v224
	v_and_b32_e32 v224, 0xffff0000, v224
	v_lshlrev_b32_e32 v137, 16, v225
	v_and_b32_e32 v225, 0xffff0000, v225
	v_lshlrev_b32_e32 v138, 16, v226
	v_and_b32_e32 v226, 0xffff0000, v226
	v_lshlrev_b32_e32 v139, 16, v227
	v_and_b32_e32 v227, 0xffff0000, v227
	v_lshlrev_b32_e32 v140, 16, v228
	v_and_b32_e32 v228, 0xffff0000, v228
	v_lshlrev_b32_e32 v141, 16, v229
	v_and_b32_e32 v229, 0xffff0000, v229
	v_lshlrev_b32_e32 v142, 16, v230
	v_and_b32_e32 v230, 0xffff0000, v230
	v_lshlrev_b32_e32 v143, 16, v231
	v_and_b32_e32 v231, 0xffff0000, v231
	v_lshlrev_b32_e32 v144, 16, v232
	v_and_b32_e32 v232, 0xffff0000, v232
	v_lshlrev_b32_e32 v145, 16, v233
	v_and_b32_e32 v233, 0xffff0000, v233
	v_fma_f32 v140, s59, v140, -v134
	v_fma_f32 v228, s59, v228, -v222
	v_fma_f32 v141, s59, v141, -v135
	v_fma_f32 v229, s59, v229, -v223
	v_fmac_f32_e32 v134, v210, v140
	v_fmac_f32_e32 v222, v211, v228
	v_fmac_f32_e32 v135, v212, v141
	v_fmac_f32_e32 v223, v213, v229
	v_fma_f32 v142, s59, v142, -v136
	v_fma_f32 v230, s59, v230, -v224
	v_fma_f32 v143, s59, v143, -v137
	v_fma_f32 v231, s59, v231, -v225
	v_fmac_f32_e32 v136, v214, v142
	v_fmac_f32_e32 v224, v215, v230
	v_fmac_f32_e32 v137, v216, v143
	v_fmac_f32_e32 v225, v217, v231
	v_fma_f32 v144, s59, v144, -v138
	v_fma_f32 v232, s59, v232, -v226
	v_fma_f32 v145, s59, v145, -v139
	v_fma_f32 v233, s59, v233, -v227
	v_fmac_f32_e32 v138, v218, v144
	v_fmac_f32_e32 v226, v219, v232
	v_fmac_f32_e32 v139, v220, v145
	v_fmac_f32_e32 v227, v221, v233
	v_mul_f32_e32 v148, v198, v136
	v_mul_f32_e32 v149, v199, v224
	v_mul_f32_e32 v150, v200, v137
	v_mul_f32_e32 v151, v201, v225
	v_mul_f32_e32 v176, v148, v148
	v_fmac_f32_e32 v176, v149, v149
	v_fmac_f32_e32 v176, v150, v150
	v_fmac_f32_e32 v176, v151, v151
	s_waitcnt lgkmcnt(2)
	v_add_f32_e32 v26, v194, v26
	v_add_f32_e32 v27, v195, v27
	v_add_f32_e32 v28, v196, v28
	v_add_f32_e32 v29, v197, v29
	v_add_f32_dpp v176, v176, v176 quad_perm:[1,0,3,2] row_mask:0xf bank_mask:0xf bound_ctrl:1
	v_mul_f32_e32 v26, 0xbfb8aa3b, v26
	v_mul_f32_e32 v27, 0xbfb8aa3b, v27
	v_mul_f32_e32 v28, 0xbfb8aa3b, v28
	v_mul_f32_e32 v29, 0xbfb8aa3b, v29
	v_add_f32_dpp v176, v176, v176 quad_perm:[2,3,0,1] row_mask:0xf bank_mask:0xf bound_ctrl:1
	v_exp_f32_e32 v26, v26
	v_exp_f32_e32 v27, v27
	v_exp_f32_e32 v28, v28
	v_exp_f32_e32 v29, v29
	v_add_f32_dpp v176, v176, v176 row_half_mirror row_mask:0xf bank_mask:0xf bound_ctrl:1
	v_add_f32_e32 v26, 1.0, v26
	v_add_f32_e32 v27, 1.0, v27
	v_add_f32_e32 v28, 1.0, v28
	v_add_f32_e32 v29, 1.0, v29
	v_add_f32_dpp v176, v176, v176 row_mirror row_mask:0xf bank_mask:0xf bound_ctrl:1
	v_rcp_f32_e32 v26, v26
	v_rcp_f32_e32 v27, v27
	v_rcp_f32_e32 v28, v28
	v_rcp_f32_e32 v29, v29
	v_sqrt_f32_e32 v176, v176
	v_add_f32_e32 v22, v190, v22
	v_add_f32_e32 v23, v191, v23
	v_add_f32_e32 v24, v192, v24
	v_add_f32_e32 v25, v193, v25
	v_max_f32_e32 v176, 0x2b8cbccc, v176
	v_mul_f32_e32 v22, 0xbfb8aa3b, v22
	v_mul_f32_e32 v23, 0xbfb8aa3b, v23
	v_mul_f32_e32 v24, 0xbfb8aa3b, v24
	v_mul_f32_e32 v25, 0xbfb8aa3b, v25
	v_rcp_f32_e32 v178, v176
	v_exp_f32_e32 v22, v22
	v_exp_f32_e32 v23, v23
	v_exp_f32_e32 v24, v24
	v_exp_f32_e32 v25, v25
	v_add_f32_e32 v22, 1.0, v22
	v_add_f32_e32 v23, 1.0, v23
	v_add_f32_e32 v24, 1.0, v24
	v_add_f32_e32 v25, 1.0, v25
	v_rcp_f32_e32 v22, v22
	v_rcp_f32_e32 v23, v23
	v_rcp_f32_e32 v24, v24
	v_rcp_f32_e32 v25, v25
	v_mul_f32_e32 v22, 0xbf1b4598, v22
	v_mul_f32_e32 v23, 0xbf1b4598, v23
	v_mul_f32_e32 v24, 0xbf1b4598, v24
	v_mul_f32_e32 v25, 0xbf1b4598, v25
	v_mul_f32_e32 v22, 0x3fb8aa3b, v22
	v_mul_f32_e32 v23, 0x3fb8aa3b, v23
	v_mul_f32_e32 v24, 0x3fb8aa3b, v24
	v_mul_f32_e32 v25, 0x3fb8aa3b, v25
	v_exp_f32_e32 v22, v22
	v_exp_f32_e32 v23, v23
	v_exp_f32_e32 v24, v24
	v_exp_f32_e32 v25, v25
	v_add_f32_e32 v152, -1.0, v26
	v_add_f32_e32 v153, -1.0, v27
	v_add_f32_e32 v154, -1.0, v28
	v_add_f32_e32 v155, -1.0, v29
	v_fma_f32 v152, v202, v152, 1.0
	v_fma_f32 v153, v203, v153, 1.0
	v_fma_f32 v154, v204, v154, 1.0
	v_fma_f32 v155, v205, v155, 1.0
	v_mul_f32_e32 v152, v136, v152
	v_mul_f32_e32 v153, v224, v153
	v_mul_f32_e32 v154, v137, v154
	v_mul_f32_e32 v155, v225, v155
	v_mul_f32_e32 v156, v134, v152
	v_mul_f32_e32 v157, v222, v153
	v_mul_f32_e32 v158, v135, v154
	v_mul_f32_e32 v159, v223, v155
	v_mul_f32_e32 v177, v206, v156
	v_fmac_f32_e32 v177, v207, v157
	v_fmac_f32_e32 v177, v208, v158
	v_fmac_f32_e32 v177, v209, v159
	v_mul_f32_e32 v148, v148, v178
	v_mul_f32_e32 v149, v149, v178
	v_add_f32_dpp v177, v177, v177 quad_perm:[1,0,3,2] row_mask:0xf bank_mask:0xf bound_ctrl:1
	v_mul_f32_e32 v150, v150, v178
	v_mul_f32_e32 v151, v151, v178
	v_add_f32_dpp v177, v177, v177 quad_perm:[2,3,0,1] row_mask:0xf bank_mask:0xf bound_ctrl:1
	v_mul_f32_e32 v26, v26, v148
	v_mul_f32_e32 v27, v27, v149
	v_add_f32_dpp v177, v177, v177 row_half_mirror row_mask:0xf bank_mask:0xf bound_ctrl:1
	v_mul_f32_e32 v28, v28, v150
	v_mul_f32_e32 v29, v29, v151
	v_add_f32_dpp v177, v177, v177 row_mirror row_mask:0xf bank_mask:0xf bound_ctrl:1
	s_lshl_b32 s0, s56, 9
	s_add_u32 s62, s34, s0
	s_addc_u32 s63, s35, 0
	v_mul_f32_e32 v156, v138, v177
	v_mul_f32_e32 v157, v226, v177
	v_mul_f32_e32 v158, v139, v177
	v_mul_f32_e32 v159, v227, v177
	v_cvt_pk_bf16_f32 v72, v134, v222
	v_cvt_pk_bf16_f32 v73, v135, v223
	global_store_dwordx2 v250, v[72:73], s[62:63]
	v_cvt_pk_bf16_f32 v74, v22, v23
	v_cvt_pk_bf16_f32 v75, v24, v25
	s_add_u32 s0, s62, 0x500000
	s_addc_u32 s1, s63, 0
	global_store_dwordx2 v250, v[74:75], s[0:1]
	v_cvt_pk_bf16_f32 v180, v152, v153
	v_cvt_pk_bf16_f32 v181, v154, v155
	s_add_u32 s0, s62, 0xa00000
	s_addc_u32 s1, s63, 0
	global_store_dwordx2 v250, v[180:181], s[0:1]
	v_cvt_pk_bf16_f32 v72, v138, v226
	v_cvt_pk_bf16_f32 v73, v139, v227
	s_add_u32 s0, s62, 0xf00000
	s_addc_u32 s1, s63, 0
	global_store_dwordx2 v250, v[72:73], s[0:1]
	v_cvt_pk_bf16_f32 v74, v148, v149
	v_cvt_pk_bf16_f32 v75, v150, v151
	s_add_u32 s0, s62, 0x1400000
	s_addc_u32 s1, s63, 0
	global_store_dwordx2 v250, v[74:75], s[0:1]
	v_cvt_pk_bf16_f32 v180, v26, v27
	v_cvt_pk_bf16_f32 v181, v28, v29
	s_add_u32 s0, s62, 0x1900000
	s_addc_u32 s1, s63, 0
	global_store_dwordx2 v250, v[180:181], s[0:1]
	v_cvt_pk_bf16_f32 v72, v156, v157
	v_cvt_pk_bf16_f32 v73, v158, v159
	s_lshl_b32 s0, s56, 9
	s_add_u32 s0, s42, s0
	s_addc_u32 s1, s43, 0
	global_store_dwordx2 v250, v[72:73], s[0:1]
	s_waitcnt vmcnt(14)
	v_lshlrev_b32_e32 v134, 16, v236
	v_and_b32_e32 v236, 0xffff0000, v236
	v_lshlrev_b32_e32 v135, 16, v237
	v_and_b32_e32 v237, 0xffff0000, v237
	v_lshlrev_b32_e32 v136, 16, v238
	v_and_b32_e32 v238, 0xffff0000, v238
	v_lshlrev_b32_e32 v137, 16, v239
	v_and_b32_e32 v239, 0xffff0000, v239
	v_lshlrev_b32_e32 v138, 16, v240
	v_and_b32_e32 v240, 0xffff0000, v240
	v_lshlrev_b32_e32 v139, 16, v241
	v_and_b32_e32 v241, 0xffff0000, v241
	v_lshlrev_b32_e32 v140, 16, v242
	v_and_b32_e32 v242, 0xffff0000, v242
	v_lshlrev_b32_e32 v141, 16, v243
	v_and_b32_e32 v243, 0xffff0000, v243
	v_lshlrev_b32_e32 v142, 16, v244
	v_and_b32_e32 v244, 0xffff0000, v244
	v_lshlrev_b32_e32 v143, 16, v245
	v_and_b32_e32 v245, 0xffff0000, v245
	v_lshlrev_b32_e32 v144, 16, v246
	v_and_b32_e32 v246, 0xffff0000, v246
	v_lshlrev_b32_e32 v145, 16, v247
	v_and_b32_e32 v247, 0xffff0000, v247
	v_fma_f32 v140, s60, v140, -v134
	v_fma_f32 v242, s60, v242, -v236
	v_fma_f32 v141, s60, v141, -v135
	v_fma_f32 v243, s60, v243, -v237
	v_fmac_f32_e32 v134, v210, v140
	v_fmac_f32_e32 v236, v211, v242
	v_fmac_f32_e32 v135, v212, v141
	v_fmac_f32_e32 v237, v213, v243
	v_fma_f32 v142, s60, v142, -v136
	v_fma_f32 v244, s60, v244, -v238
	v_fma_f32 v143, s60, v143, -v137
	v_fma_f32 v245, s60, v245, -v239
	v_fmac_f32_e32 v136, v214, v142
	v_fmac_f32_e32 v238, v215, v244
	v_fmac_f32_e32 v137, v216, v143
	v_fmac_f32_e32 v239, v217, v245
	v_fma_f32 v144, s60, v144, -v138
	v_fma_f32 v246, s60, v246, -v240
	v_fma_f32 v145, s60, v145, -v139
	v_fma_f32 v247, s60, v247, -v241
	v_fmac_f32_e32 v138, v218, v144
	v_fmac_f32_e32 v240, v219, v246
	v_fmac_f32_e32 v139, v220, v145
	v_fmac_f32_e32 v241, v221, v247
	v_mul_f32_e32 v148, v198, v136
	v_mul_f32_e32 v149, v199, v238
	v_mul_f32_e32 v150, v200, v137
	v_mul_f32_e32 v151, v201, v239
	v_mul_f32_e32 v176, v148, v148
	v_fmac_f32_e32 v176, v149, v149
	v_fmac_f32_e32 v176, v150, v150
	v_fmac_f32_e32 v176, v151, v151
	s_waitcnt lgkmcnt(0)
	v_add_f32_e32 v18, v194, v18
	v_add_f32_e32 v19, v195, v19
	v_add_f32_e32 v20, v196, v20
	v_add_f32_e32 v21, v197, v21
	v_add_f32_dpp v176, v176, v176 quad_perm:[1,0,3,2] row_mask:0xf bank_mask:0xf bound_ctrl:1
	v_mul_f32_e32 v18, 0xbfb8aa3b, v18
	v_mul_f32_e32 v19, 0xbfb8aa3b, v19
	v_mul_f32_e32 v20, 0xbfb8aa3b, v20
	v_mul_f32_e32 v21, 0xbfb8aa3b, v21
	v_add_f32_dpp v176, v176, v176 quad_perm:[2,3,0,1] row_mask:0xf bank_mask:0xf bound_ctrl:1
	v_exp_f32_e32 v18, v18
	v_exp_f32_e32 v19, v19
	v_exp_f32_e32 v20, v20
	v_exp_f32_e32 v21, v21
	v_add_f32_dpp v176, v176, v176 row_half_mirror row_mask:0xf bank_mask:0xf bound_ctrl:1
	v_add_f32_e32 v18, 1.0, v18
	v_add_f32_e32 v19, 1.0, v19
	v_add_f32_e32 v20, 1.0, v20
	v_add_f32_e32 v21, 1.0, v21
	v_add_f32_dpp v176, v176, v176 row_mirror row_mask:0xf bank_mask:0xf bound_ctrl:1
	v_rcp_f32_e32 v18, v18
	v_rcp_f32_e32 v19, v19
	v_rcp_f32_e32 v20, v20
	v_rcp_f32_e32 v21, v21
	v_sqrt_f32_e32 v176, v176
	v_add_f32_e32 v14, v190, v14
	v_add_f32_e32 v15, v191, v15
	v_add_f32_e32 v16, v192, v16
	v_add_f32_e32 v17, v193, v17
	v_max_f32_e32 v176, 0x2b8cbccc, v176
	v_mul_f32_e32 v14, 0xbfb8aa3b, v14
	v_mul_f32_e32 v15, 0xbfb8aa3b, v15
	v_mul_f32_e32 v16, 0xbfb8aa3b, v16
	v_mul_f32_e32 v17, 0xbfb8aa3b, v17
	v_rcp_f32_e32 v178, v176
	v_exp_f32_e32 v14, v14
	v_exp_f32_e32 v15, v15
	v_exp_f32_e32 v16, v16
	v_exp_f32_e32 v17, v17
	v_add_f32_e32 v14, 1.0, v14
	v_add_f32_e32 v15, 1.0, v15
	v_add_f32_e32 v16, 1.0, v16
	v_add_f32_e32 v17, 1.0, v17
	v_rcp_f32_e32 v14, v14
	v_rcp_f32_e32 v15, v15
	v_rcp_f32_e32 v16, v16
	v_rcp_f32_e32 v17, v17
	v_mul_f32_e32 v14, 0xbf1b4598, v14
	v_mul_f32_e32 v15, 0xbf1b4598, v15
	v_mul_f32_e32 v16, 0xbf1b4598, v16
	v_mul_f32_e32 v17, 0xbf1b4598, v17
	v_mul_f32_e32 v14, 0x3fb8aa3b, v14
	v_mul_f32_e32 v15, 0x3fb8aa3b, v15
	v_mul_f32_e32 v16, 0x3fb8aa3b, v16
	v_mul_f32_e32 v17, 0x3fb8aa3b, v17
	v_exp_f32_e32 v14, v14
	v_exp_f32_e32 v15, v15
	v_exp_f32_e32 v16, v16
	v_exp_f32_e32 v17, v17
	v_add_f32_e32 v152, -1.0, v18
	v_add_f32_e32 v153, -1.0, v19
	v_add_f32_e32 v154, -1.0, v20
	v_add_f32_e32 v155, -1.0, v21
	v_fma_f32 v152, v202, v152, 1.0
	v_fma_f32 v153, v203, v153, 1.0
	v_fma_f32 v154, v204, v154, 1.0
	v_fma_f32 v155, v205, v155, 1.0
	v_mul_f32_e32 v152, v136, v152
	v_mul_f32_e32 v153, v238, v153
	v_mul_f32_e32 v154, v137, v154
	v_mul_f32_e32 v155, v239, v155
	v_mul_f32_e32 v156, v134, v152
	v_mul_f32_e32 v157, v236, v153
	v_mul_f32_e32 v158, v135, v154
	v_mul_f32_e32 v159, v237, v155
	v_mul_f32_e32 v177, v206, v156
	v_fmac_f32_e32 v177, v207, v157
	v_fmac_f32_e32 v177, v208, v158
	v_fmac_f32_e32 v177, v209, v159
	v_mul_f32_e32 v148, v148, v178
	v_mul_f32_e32 v149, v149, v178
	v_add_f32_dpp v177, v177, v177 quad_perm:[1,0,3,2] row_mask:0xf bank_mask:0xf bound_ctrl:1
	v_mul_f32_e32 v150, v150, v178
	v_mul_f32_e32 v151, v151, v178
	v_add_f32_dpp v177, v177, v177 quad_perm:[2,3,0,1] row_mask:0xf bank_mask:0xf bound_ctrl:1
	v_mul_f32_e32 v18, v18, v148
	v_mul_f32_e32 v19, v19, v149
	v_add_f32_dpp v177, v177, v177 row_half_mirror row_mask:0xf bank_mask:0xf bound_ctrl:1
	v_mul_f32_e32 v20, v20, v150
	v_mul_f32_e32 v21, v21, v151
	v_add_f32_dpp v177, v177, v177 row_mirror row_mask:0xf bank_mask:0xf bound_ctrl:1
	s_lshl_b32 s0, s57, 9
	s_add_u32 s62, s34, s0
	s_addc_u32 s63, s35, 0
	v_mul_f32_e32 v156, v138, v177
	v_mul_f32_e32 v157, v240, v177
	v_mul_f32_e32 v158, v139, v177
	v_mul_f32_e32 v159, v241, v177
	v_cvt_pk_bf16_f32 v72, v134, v236
	v_cvt_pk_bf16_f32 v73, v135, v237
	global_store_dwordx2 v250, v[72:73], s[62:63]
	v_cvt_pk_bf16_f32 v74, v14, v15
	v_cvt_pk_bf16_f32 v75, v16, v17
	s_add_u32 s0, s62, 0x500000
	s_addc_u32 s1, s63, 0
	global_store_dwordx2 v250, v[74:75], s[0:1]
	v_cvt_pk_bf16_f32 v180, v152, v153
	v_cvt_pk_bf16_f32 v181, v154, v155
	s_add_u32 s0, s62, 0xa00000
	s_addc_u32 s1, s63, 0
	global_store_dwordx2 v250, v[180:181], s[0:1]
	v_cvt_pk_bf16_f32 v72, v138, v240
	v_cvt_pk_bf16_f32 v73, v139, v241
	s_add_u32 s0, s62, 0xf00000
	s_addc_u32 s1, s63, 0
	global_store_dwordx2 v250, v[72:73], s[0:1]
	v_cvt_pk_bf16_f32 v74, v148, v149
	v_cvt_pk_bf16_f32 v75, v150, v151
	s_add_u32 s0, s62, 0x1400000
	s_addc_u32 s1, s63, 0
	global_store_dwordx2 v250, v[74:75], s[0:1]
	v_cvt_pk_bf16_f32 v180, v18, v19
	v_cvt_pk_bf16_f32 v181, v20, v21
	s_add_u32 s0, s62, 0x1900000
	s_addc_u32 s1, s63, 0
	global_store_dwordx2 v250, v[180:181], s[0:1]
	v_cvt_pk_bf16_f32 v72, v156, v157
	v_cvt_pk_bf16_f32 v73, v158, v159
	s_lshl_b32 s0, s57, 9
	s_add_u32 s0, s42, s0
	s_addc_u32 s1, s43, 0
	global_store_dwordx2 v250, v[72:73], s[0:1]
	s_branch .LBB0_476
.Lprep_tok_d1:
	ds_read_b128 v[210:213], v251 offset:53248
	ds_read_b128 v[214:217], v251 offset:54272
	ds_read_b128 v[218:221], v251 offset:55296
	ds_read_b128 v[198:201], v251 offset:56320
	ds_read_b128 v[194:197], v251 offset:57344
	ds_read_b128 v[190:193], v251 offset:58368
	ds_read_b128 v[202:205], v251 offset:59392
	ds_read_b128 v[206:209], v251 offset:60416
	s_add_u32 s34, s34, 0x1e00000
	s_addc_u32 s35, s35, 0
	s_add_i32 s56, s53, 0
	s_cmpk_lt_i32 s56, 0x2000
	s_movk_i32 s0, 0x3ff
	s_cselect_b32 s0, 0xff, s0
	s_and_b32 s1, s56, s0
	s_cmp_lg_u32 s1, s0
	s_cselect_b32 s59, 1.0, 0
	s_cselect_b32 s1, 1, 0
	s_add_i32 s1, s56, s1
	s_mul_i32 s0, s56, 0x1d00
	s_add_u32 s76, s28, s0
	s_addc_u32 s77, s29, 0
	s_mul_i32 s0, s1, 0x1d00
	s_add_u32 s78, s28, s0
	s_addc_u32 s79, s29, 0
	global_load_dwordx2 v[222:223], v250, s[76:77] offset:0
	global_load_dwordx2 v[224:225], v250, s[76:77] offset:512
	global_load_dwordx2 v[226:227], v250, s[76:77] offset:1024
	global_load_dwordx2 v[228:229], v250, s[78:79] offset:0
	global_load_dwordx2 v[230:231], v250, s[78:79] offset:512
	global_load_dwordx2 v[232:233], v250, s[78:79] offset:1024
	s_lshl_b32 s0, s56, 9
	s_add_u32 s0, s42, s0
	s_addc_u32 s1, s43, 0
	global_load_dwordx2 v[234:235], v250, s[0:1]
	s_add_i32 s57, s53, 4
	s_cmpk_lt_i32 s57, 0x2000
	s_movk_i32 s0, 0x3ff
	s_cselect_b32 s0, 0xff, s0
	s_and_b32 s1, s57, s0
	s_cmp_lg_u32 s1, s0
	s_cselect_b32 s60, 1.0, 0
	s_cselect_b32 s1, 1, 0
	s_add_i32 s1, s57, s1
	s_mul_i32 s0, s57, 0x1d00
	s_add_u32 s80, s28, s0
	s_addc_u32 s81, s29, 0
	s_mul_i32 s0, s1, 0x1d00
	s_add_u32 s82, s28, s0
	s_addc_u32 s83, s29, 0
	global_load_dwordx2 v[236:237], v250, s[80:81] offset:0
	global_load_dwordx2 v[238:239], v250, s[80:81] offset:512
	global_load_dwordx2 v[240:241], v250, s[80:81] offset:1024
	global_load_dwordx2 v[242:243], v250, s[82:83] offset:0
	global_load_dwordx2 v[244:245], v250, s[82:83] offset:512
	global_load_dwordx2 v[246:247], v250, s[82:83] offset:1024
	s_lshl_b32 s0, s57, 9
	s_add_u32 s0, s42, s0
	s_addc_u32 s1, s43, 0
	global_load_dwordx2 v[248:249], v250, s[0:1]
	s_add_i32 s58, s53, 8
	s_cmpk_lt_i32 s58, 0x2000
	s_movk_i32 s0, 0x3ff
	s_cselect_b32 s0, 0xff, s0
	s_and_b32 s1, s58, s0
	s_cmp_lg_u32 s1, s0
	s_cselect_b32 s61, 1.0, 0
	s_cselect_b32 s1, 1, 0
	s_add_i32 s1, s58, s1
	s_mul_i32 s0, s58, 0x1d00
	s_add_u32 s84, s28, s0
	s_addc_u32 s85, s29, 0
	s_mul_i32 s0, s1, 0x1d00
	s_add_u32 s96, s28, s0
	s_addc_u32 s97, s29, 0
	global_load_dwordx2 v[0:1], v250, s[84:85] offset:0
	global_load_dwordx2 v[2:3], v250, s[84:85] offset:512
	global_load_dwordx2 v[4:5], v250, s[84:85] offset:1024
	global_load_dwordx2 v[6:7], v250, s[96:97] offset:0
	global_load_dwordx2 v[8:9], v250, s[96:97] offset:512
	global_load_dwordx2 v[10:11], v250, s[96:97] offset:1024
	s_lshl_b32 s0, s58, 9
	s_add_u32 s0, s42, s0
	s_addc_u32 s1, s43, 0
	global_load_dwordx2 v[12:13], v250, s[0:1]
	ds_read_b128 v[14:17], v31 offset:0
	ds_read_b128 v[18:21], v31 offset:20480
	ds_read_b128 v[22:25], v31 offset:4096
	ds_read_b128 v[26:29], v31 offset:24576
	s_waitcnt lgkmcnt(4)
	s_waitcnt vmcnt(14)
	v_lshlrev_b32_e32 v134, 16, v222
	v_and_b32_e32 v222, 0xffff0000, v222
	v_lshlrev_b32_e32 v135, 16, v223
	v_and_b32_e32 v223, 0xffff0000, v223
	v_lshlrev_b32_e32 v136, 16, v224
	v_and_b32_e32 v224, 0xffff0000, v224
	v_lshlrev_b32_e32 v137, 16, v225
	v_and_b32_e32 v225, 0xffff0000, v225
	v_lshlrev_b32_e32 v138, 16, v226
	v_and_b32_e32 v226, 0xffff0000, v226
	v_lshlrev_b32_e32 v139, 16, v227
	v_and_b32_e32 v227, 0xffff0000, v227
	v_lshlrev_b32_e32 v140, 16, v228
	v_and_b32_e32 v228, 0xffff0000, v228
	v_lshlrev_b32_e32 v141, 16, v229
	v_and_b32_e32 v229, 0xffff0000, v229
	v_lshlrev_b32_e32 v142, 16, v230
	v_and_b32_e32 v230, 0xffff0000, v230
	v_lshlrev_b32_e32 v143, 16, v231
	v_and_b32_e32 v231, 0xffff0000, v231
	v_lshlrev_b32_e32 v144, 16, v232
	v_and_b32_e32 v232, 0xffff0000, v232
	v_lshlrev_b32_e32 v145, 16, v233
	v_and_b32_e32 v233, 0xffff0000, v233
	v_lshlrev_b32_e32 v146, 16, v234
	v_and_b32_e32 v234, 0xffff0000, v234
	v_lshlrev_b32_e32 v147, 16, v235
	v_and_b32_e32 v235, 0xffff0000, v235
	v_fma_f32 v140, s59, v140, -v134
	v_fma_f32 v228, s59, v228, -v222
	v_fma_f32 v141, s59, v141, -v135
	v_fma_f32 v229, s59, v229, -v223
	v_fmac_f32_e32 v134, v210, v140
	v_fmac_f32_e32 v222, v211, v228
	v_fmac_f32_e32 v135, v212, v141
	v_fmac_f32_e32 v223, v213, v229
	v_fma_f32 v142, s59, v142, -v136
	v_fma_f32 v230, s59, v230, -v224
	v_fma_f32 v143, s59, v143, -v137
	v_fma_f32 v231, s59, v231, -v225
	v_fmac_f32_e32 v136, v214, v142
	v_fmac_f32_e32 v224, v215, v230
	v_fmac_f32_e32 v137, v216, v143
	v_fmac_f32_e32 v225, v217, v231
	v_fma_f32 v144, s59, v144, -v138
	v_fma_f32 v232, s59, v232, -v226
	v_fma_f32 v145, s59, v145, -v139
	v_fma_f32 v233, s59, v233, -v227
	v_fmac_f32_e32 v138, v218, v144
	v_fmac_f32_e32 v226, v219, v232
	v_fmac_f32_e32 v139, v220, v145
	v_fmac_f32_e32 v227, v221, v233
	v_mul_f32_e32 v148, v198, v136
	v_mul_f32_e32 v149, v199, v224
	v_mul_f32_e32 v150, v200, v137
	v_mul_f32_e32 v151, v201, v225
	v_mul_f32_e32 v176, v148, v148
	v_fmac_f32_e32 v176, v149, v149
	v_fmac_f32_e32 v176, v150, v150
	v_fmac_f32_e32 v176, v151, v151
	s_waitcnt lgkmcnt(2)
	v_add_f32_e32 v18, v194, v18
	v_add_f32_e32 v19, v195, v19
	v_add_f32_e32 v20, v196, v20
	v_add_f32_e32 v21, v197, v21
	v_add_f32_dpp v176, v176, v176 quad_perm:[1,0,3,2] row_mask:0xf bank_mask:0xf bound_ctrl:1
	v_mul_f32_e32 v18, 0xbfb8aa3b, v18
	v_mul_f32_e32 v19, 0xbfb8aa3b, v19
	v_mul_f32_e32 v20, 0xbfb8aa3b, v20
	v_mul_f32_e32 v21, 0xbfb8aa3b, v21
	v_add_f32_dpp v176, v176, v176 quad_perm:[2,3,0,1] row_mask:0xf bank_mask:0xf bound_ctrl:1
	v_exp_f32_e32 v18, v18
	v_exp_f32_e32 v19, v19
	v_exp_f32_e32 v20, v20
	v_exp_f32_e32 v21, v21
	v_add_f32_dpp v176, v176, v176 row_half_mirror row_mask:0xf bank_mask:0xf bound_ctrl:1
	v_add_f32_e32 v18, 1.0, v18
	v_add_f32_e32 v19, 1.0, v19
	v_add_f32_e32 v20, 1.0, v20
	v_add_f32_e32 v21, 1.0, v21
	v_add_f32_dpp v176, v176, v176 row_mirror row_mask:0xf bank_mask:0xf bound_ctrl:1
	v_rcp_f32_e32 v18, v18
	v_rcp_f32_e32 v19, v19
	v_rcp_f32_e32 v20, v20
	v_rcp_f32_e32 v21, v21
	v_sqrt_f32_e32 v176, v176
	v_add_f32_e32 v14, v190, v14
	v_add_f32_e32 v15, v191, v15
	v_add_f32_e32 v16, v192, v16
	v_add_f32_e32 v17, v193, v17
	v_max_f32_e32 v176, 0x2b8cbccc, v176
	v_mul_f32_e32 v14, 0xbfb8aa3b, v14
	v_mul_f32_e32 v15, 0xbfb8aa3b, v15
	v_mul_f32_e32 v16, 0xbfb8aa3b, v16
	v_mul_f32_e32 v17, 0xbfb8aa3b, v17
	v_rcp_f32_e32 v178, v176
	v_exp_f32_e32 v14, v14
	v_exp_f32_e32 v15, v15
	v_exp_f32_e32 v16, v16
	v_exp_f32_e32 v17, v17
	v_add_f32_e32 v14, 1.0, v14
	v_add_f32_e32 v15, 1.0, v15
	v_add_f32_e32 v16, 1.0, v16
	v_add_f32_e32 v17, 1.0, v17
	v_rcp_f32_e32 v14, v14
	v_rcp_f32_e32 v15, v15
	v_rcp_f32_e32 v16, v16
	v_rcp_f32_e32 v17, v17
	v_mul_f32_e32 v14, 0xbf1b4598, v14
	v_mul_f32_e32 v15, 0xbf1b4598, v15
	v_mul_f32_e32 v16, 0xbf1b4598, v16
	v_mul_f32_e32 v17, 0xbf1b4598, v17
	v_mul_f32_e32 v14, 0x3fb8aa3b, v14
	v_mul_f32_e32 v15, 0x3fb8aa3b, v15
	v_mul_f32_e32 v16, 0x3fb8aa3b, v16
	v_mul_f32_e32 v17, 0x3fb8aa3b, v17
	v_exp_f32_e32 v14, v14
	v_exp_f32_e32 v15, v15
	v_exp_f32_e32 v16, v16
	v_exp_f32_e32 v17, v17
	v_add_f32_e32 v152, -1.0, v18
	v_add_f32_e32 v153, -1.0, v19
	v_add_f32_e32 v154, -1.0, v20
	v_add_f32_e32 v155, -1.0, v21
	v_fma_f32 v152, v202, v152, 1.0
	v_fma_f32 v153, v203, v153, 1.0
	v_fma_f32 v154, v204, v154, 1.0
	v_fma_f32 v155, v205, v155, 1.0
	v_mul_f32_e32 v152, v136, v152
	v_mul_f32_e32 v153, v224, v153
	v_mul_f32_e32 v154, v137, v154
	v_mul_f32_e32 v155, v225, v155
	v_mul_f32_e32 v156, v134, v152
	v_mul_f32_e32 v157, v222, v153
	v_mul_f32_e32 v158, v135, v154
	v_mul_f32_e32 v159, v223, v155
	v_mul_f32_e32 v177, v206, v156
	v_fmac_f32_e32 v177, v207, v157
	v_fmac_f32_e32 v177, v208, v158
	v_fmac_f32_e32 v177, v209, v159
	v_mul_f32_e32 v148, v148, v178
	v_mul_f32_e32 v149, v149, v178
	v_add_f32_dpp v177, v177, v177 quad_perm:[1,0,3,2] row_mask:0xf bank_mask:0xf bound_ctrl:1
	v_mul_f32_e32 v150, v150, v178
	v_mul_f32_e32 v151, v151, v178
	v_add_f32_dpp v177, v177, v177 quad_perm:[2,3,0,1] row_mask:0xf bank_mask:0xf bound_ctrl:1
	v_mul_f32_e32 v18, v18, v148
	v_mul_f32_e32 v19, v19, v149
	v_add_f32_dpp v177, v177, v177 row_half_mirror row_mask:0xf bank_mask:0xf bound_ctrl:1
	v_mul_f32_e32 v20, v20, v150
	v_mul_f32_e32 v21, v21, v151
	v_add_f32_dpp v177, v177, v177 row_mirror row_mask:0xf bank_mask:0xf bound_ctrl:1
	s_lshl_b32 s0, s56, 9
	s_add_u32 s62, s34, s0
	s_addc_u32 s63, s35, 0
	v_fmac_f32_e32 v146, v138, v177
	v_fmac_f32_e32 v234, v226, v177
	v_fmac_f32_e32 v147, v139, v177
	v_fmac_f32_e32 v235, v227, v177
	v_cvt_pk_bf16_f32 v72, v134, v222
	v_cvt_pk_bf16_f32 v73, v135, v223
	global_store_dwordx2 v250, v[72:73], s[62:63]
	v_cvt_pk_bf16_f32 v74, v14, v15
	v_cvt_pk_bf16_f32 v75, v16, v17
	s_add_u32 s0, s62, 0x500000
	s_addc_u32 s1, s63, 0
	global_store_dwordx2 v250, v[74:75], s[0:1]
	v_cvt_pk_bf16_f32 v180, v152, v153
	v_cvt_pk_bf16_f32 v181, v154, v155
	s_add_u32 s0, s62, 0xa00000
	s_addc_u32 s1, s63, 0
	global_store_dwordx2 v250, v[180:181], s[0:1]
	v_cvt_pk_bf16_f32 v72, v138, v226
	v_cvt_pk_bf16_f32 v73, v139, v227
	s_add_u32 s0, s62, 0xf00000
	s_addc_u32 s1, s63, 0
	global_store_dwordx2 v250, v[72:73], s[0:1]
	v_cvt_pk_bf16_f32 v74, v148, v149
	v_cvt_pk_bf16_f32 v75, v150, v151
	s_add_u32 s0, s62, 0x1400000
	s_addc_u32 s1, s63, 0
	global_store_dwordx2 v250, v[74:75], s[0:1]
	v_cvt_pk_bf16_f32 v180, v18, v19
	v_cvt_pk_bf16_f32 v181, v20, v21
	s_add_u32 s0, s62, 0x1900000
	s_addc_u32 s1, s63, 0
	global_store_dwordx2 v250, v[180:181], s[0:1]
	v_cvt_pk_bf16_f32 v72, v146, v234
	v_cvt_pk_bf16_f32 v73, v147, v235
	s_lshl_b32 s0, s56, 9
	s_add_u32 s0, s42, s0
	s_addc_u32 s1, s43, 0
	global_store_dwordx2 v250, v[72:73], s[0:1]
	s_add_i32 s56, s53, 12
	s_cmpk_lt_i32 s56, 0x2000
	s_movk_i32 s0, 0x3ff
	s_cselect_b32 s0, 0xff, s0
	s_and_b32 s1, s56, s0
	s_cmp_lg_u32 s1, s0
	s_cselect_b32 s59, 1.0, 0
	s_cselect_b32 s1, 1, 0
	s_add_i32 s1, s56, s1
	s_mul_i32 s0, s56, 0x1d00
	s_add_u32 s76, s28, s0
	s_addc_u32 s77, s29, 0
	s_mul_i32 s0, s1, 0x1d00
	s_add_u32 s78, s28, s0
	s_addc_u32 s79, s29, 0
	global_load_dwordx2 v[222:223], v250, s[76:77] offset:0
	global_load_dwordx2 v[224:225], v250, s[76:77] offset:512
	global_load_dwordx2 v[226:227], v250, s[76:77] offset:1024
	global_load_dwordx2 v[228:229], v250, s[78:79] offset:0
	global_load_dwordx2 v[230:231], v250, s[78:79] offset:512
	global_load_dwordx2 v[232:233], v250, s[78:79] offset:1024
	s_lshl_b32 s0, s56, 9
	s_add_u32 s0, s42, s0
	s_addc_u32 s1, s43, 0
	global_load_dwordx2 v[234:235], v250, s[0:1]
	ds_read_b128 v[14:17], v31 offset:8192
	ds_read_b128 v[18:21], v31 offset:28672
	s_waitcnt vmcnt(21)
	v_lshlrev_b32_e32 v134, 16, v236
	v_and_b32_e32 v236, 0xffff0000, v236
	v_lshlrev_b32_e32 v135, 16, v237
	v_and_b32_e32 v237, 0xffff0000, v237
	v_lshlrev_b32_e32 v136, 16, v238
	v_and_b32_e32 v238, 0xffff0000, v238
	v_lshlrev_b32_e32 v137, 16, v239
	v_and_b32_e32 v239, 0xffff0000, v239
	v_lshlrev_b32_e32 v138, 16, v240
	v_and_b32_e32 v240, 0xffff0000, v240
	v_lshlrev_b32_e32 v139, 16, v241
	v_and_b32_e32 v241, 0xffff0000, v241
	v_lshlrev_b32_e32 v140, 16, v242
	v_and_b32_e32 v242, 0xffff0000, v242
	v_lshlrev_b32_e32 v141, 16, v243
	v_and_b32_e32 v243, 0xffff0000, v243
	v_lshlrev_b32_e32 v142, 16, v244
	v_and_b32_e32 v244, 0xffff0000, v244
	v_lshlrev_b32_e32 v143, 16, v245
	v_and_b32_e32 v245, 0xffff0000, v245
	v_lshlrev_b32_e32 v144, 16, v246
	v_and_b32_e32 v246, 0xffff0000, v246
	v_lshlrev_b32_e32 v145, 16, v247
	v_and_b32_e32 v247, 0xffff0000, v247
	v_lshlrev_b32_e32 v146, 16, v248
	v_and_b32_e32 v248, 0xffff0000, v248
	v_lshlrev_b32_e32 v147, 16, v249
	v_and_b32_e32 v249, 0xffff0000, v249
	v_fma_f32 v140, s60, v140, -v134
	v_fma_f32 v242, s60, v242, -v236
	v_fma_f32 v141, s60, v141, -v135
	v_fma_f32 v243, s60, v243, -v237
	v_fmac_f32_e32 v134, v210, v140
	v_fmac_f32_e32 v236, v211, v242
	v_fmac_f32_e32 v135, v212, v141
	v_fmac_f32_e32 v237, v213, v243
	v_fma_f32 v142, s60, v142, -v136
	v_fma_f32 v244, s60, v244, -v238
	v_fma_f32 v143, s60, v143, -v137
	v_fma_f32 v245, s60, v245, -v239
	v_fmac_f32_e32 v136, v214, v142
	v_fmac_f32_e32 v238, v215, v244
	v_fmac_f32_e32 v137, v216, v143
	v_fmac_f32_e32 v239, v217, v245
	v_fma_f32 v144, s60, v144, -v138
	v_fma_f32 v246, s60, v246, -v240
	v_fma_f32 v145, s60, v145, -v139
	v_fma_f32 v247, s60, v247, -v241
	v_fmac_f32_e32 v138, v218, v144
	v_fmac_f32_e32 v240, v219, v246
	v_fmac_f32_e32 v139, v220, v145
	v_fmac_f32_e32 v241, v221, v247
	v_mul_f32_e32 v148, v198, v136
	v_mul_f32_e32 v149, v199, v238
	v_mul_f32_e32 v150, v200, v137
	v_mul_f32_e32 v151, v201, v239
	v_mul_f32_e32 v176, v148, v148
	v_fmac_f32_e32 v176, v149, v149
	v_fmac_f32_e32 v176, v150, v150
	v_fmac_f32_e32 v176, v151, v151
	s_waitcnt lgkmcnt(2)
	v_add_f32_e32 v26, v194, v26
	v_add_f32_e32 v27, v195, v27
	v_add_f32_e32 v28, v196, v28
	v_add_f32_e32 v29, v197, v29
	v_add_f32_dpp v176, v176, v176 quad_perm:[1,0,3,2] row_mask:0xf bank_mask:0xf bound_ctrl:1
	v_mul_f32_e32 v26, 0xbfb8aa3b, v26
	v_mul_f32_e32 v27, 0xbfb8aa3b, v27
	v_mul_f32_e32 v28, 0xbfb8aa3b, v28
	v_mul_f32_e32 v29, 0xbfb8aa3b, v29
	v_add_f32_dpp v176, v176, v176 quad_perm:[2,3,0,1] row_mask:0xf bank_mask:0xf bound_ctrl:1
	v_exp_f32_e32 v26, v26
	v_exp_f32_e32 v27, v27
	v_exp_f32_e32 v28, v28
	v_exp_f32_e32 v29, v29
	v_add_f32_dpp v176, v176, v176 row_half_mirror row_mask:0xf bank_mask:0xf bound_ctrl:1
	v_add_f32_e32 v26, 1.0, v26
	v_add_f32_e32 v27, 1.0, v27
	v_add_f32_e32 v28, 1.0, v28
	v_add_f32_e32 v29, 1.0, v29
	v_add_f32_dpp v176, v176, v176 row_mirror row_mask:0xf bank_mask:0xf bound_ctrl:1
	v_rcp_f32_e32 v26, v26
	v_rcp_f32_e32 v27, v27
	v_rcp_f32_e32 v28, v28
	v_rcp_f32_e32 v29, v29
	v_sqrt_f32_e32 v176, v176
	v_add_f32_e32 v22, v190, v22
	v_add_f32_e32 v23, v191, v23
	v_add_f32_e32 v24, v192, v24
	v_add_f32_e32 v25, v193, v25
	v_max_f32_e32 v176, 0x2b8cbccc, v176
	v_mul_f32_e32 v22, 0xbfb8aa3b, v22
	v_mul_f32_e32 v23, 0xbfb8aa3b, v23
	v_mul_f32_e32 v24, 0xbfb8aa3b, v24
	v_mul_f32_e32 v25, 0xbfb8aa3b, v25
	v_rcp_f32_e32 v178, v176
	v_exp_f32_e32 v22, v22
	v_exp_f32_e32 v23, v23
	v_exp_f32_e32 v24, v24
	v_exp_f32_e32 v25, v25
	v_add_f32_e32 v22, 1.0, v22
	v_add_f32_e32 v23, 1.0, v23
	v_add_f32_e32 v24, 1.0, v24
	v_add_f32_e32 v25, 1.0, v25
	v_rcp_f32_e32 v22, v22
	v_rcp_f32_e32 v23, v23
	v_rcp_f32_e32 v24, v24
	v_rcp_f32_e32 v25, v25
	v_mul_f32_e32 v22, 0xbf1b4598, v22
	v_mul_f32_e32 v23, 0xbf1b4598, v23
	v_mul_f32_e32 v24, 0xbf1b4598, v24
	v_mul_f32_e32 v25, 0xbf1b4598, v25
	v_mul_f32_e32 v22, 0x3fb8aa3b, v22
	v_mul_f32_e32 v23, 0x3fb8aa3b, v23
	v_mul_f32_e32 v24, 0x3fb8aa3b, v24
	v_mul_f32_e32 v25, 0x3fb8aa3b, v25
	v_exp_f32_e32 v22, v22
	v_exp_f32_e32 v23, v23
	v_exp_f32_e32 v24, v24
	v_exp_f32_e32 v25, v25
	v_add_f32_e32 v152, -1.0, v26
	v_add_f32_e32 v153, -1.0, v27
	v_add_f32_e32 v154, -1.0, v28
	v_add_f32_e32 v155, -1.0, v29
	v_fma_f32 v152, v202, v152, 1.0
	v_fma_f32 v153, v203, v153, 1.0
	v_fma_f32 v154, v204, v154, 1.0
	v_fma_f32 v155, v205, v155, 1.0
	v_mul_f32_e32 v152, v136, v152
	v_mul_f32_e32 v153, v238, v153
	v_mul_f32_e32 v154, v137, v154
	v_mul_f32_e32 v155, v239, v155
	v_mul_f32_e32 v156, v134, v152
	v_mul_f32_e32 v157, v236, v153
	v_mul_f32_e32 v158, v135, v154
	v_mul_f32_e32 v159, v237, v155
	v_mul_f32_e32 v177, v206, v156
	v_fmac_f32_e32 v177, v207, v157
	v_fmac_f32_e32 v177, v208, v158
	v_fmac_f32_e32 v177, v209, v159
	v_mul_f32_e32 v148, v148, v178
	v_mul_f32_e32 v149, v149, v178
	v_add_f32_dpp v177, v177, v177 quad_perm:[1,0,3,2] row_mask:0xf bank_mask:0xf bound_ctrl:1
	v_mul_f32_e32 v150, v150, v178
	v_mul_f32_e32 v151, v151, v178
	v_add_f32_dpp v177, v177, v177 quad_perm:[2,3,0,1] row_mask:0xf bank_mask:0xf bound_ctrl:1
	v_mul_f32_e32 v26, v26, v148
	v_mul_f32_e32 v27, v27, v149
	v_add_f32_dpp v177, v177, v177 row_half_mirror row_mask:0xf bank_mask:0xf bound_ctrl:1
	v_mul_f32_e32 v28, v28, v150
	v_mul_f32_e32 v29, v29, v151
	v_add_f32_dpp v177, v177, v177 row_mirror row_mask:0xf bank_mask:0xf bound_ctrl:1
	s_lshl_b32 s0, s57, 9
	s_add_u32 s62, s34, s0
	s_addc_u32 s63, s35, 0
	v_fmac_f32_e32 v146, v138, v177
	v_fmac_f32_e32 v248, v240, v177
	v_fmac_f32_e32 v147, v139, v177
	v_fmac_f32_e32 v249, v241, v177
	v_cvt_pk_bf16_f32 v72, v134, v236
	v_cvt_pk_bf16_f32 v73, v135, v237
	global_store_dwordx2 v250, v[72:73], s[62:63]
	v_cvt_pk_bf16_f32 v74, v22, v23
	v_cvt_pk_bf16_f32 v75, v24, v25
	s_add_u32 s0, s62, 0x500000
	s_addc_u32 s1, s63, 0
	global_store_dwordx2 v250, v[74:75], s[0:1]
	v_cvt_pk_bf16_f32 v180, v152, v153
	v_cvt_pk_bf16_f32 v181, v154, v155
	s_add_u32 s0, s62, 0xa00000
	s_addc_u32 s1, s63, 0
	global_store_dwordx2 v250, v[180:181], s[0:1]
	v_cvt_pk_bf16_f32 v72, v138, v240
	v_cvt_pk_bf16_f32 v73, v139, v241
	s_add_u32 s0, s62, 0xf00000
	s_addc_u32 s1, s63, 0
	global_store_dwordx2 v250, v[72:73], s[0:1]
	v_cvt_pk_bf16_f32 v74, v148, v149
	v_cvt_pk_bf16_f32 v75, v150, v151
	s_add_u32 s0, s62, 0x1400000
	s_addc_u32 s1, s63, 0
	global_store_dwordx2 v250, v[74:75], s[0:1]
	v_cvt_pk_bf16_f32 v180, v26, v27
	v_cvt_pk_bf16_f32 v181, v28, v29
	s_add_u32 s0, s62, 0x1900000
	s_addc_u32 s1, s63, 0
	global_store_dwordx2 v250, v[180:181], s[0:1]
	v_cvt_pk_bf16_f32 v72, v146, v248
	v_cvt_pk_bf16_f32 v73, v147, v249
	s_lshl_b32 s0, s57, 9
	s_add_u32 s0, s42, s0
	s_addc_u32 s1, s43, 0
	global_store_dwordx2 v250, v[72:73], s[0:1]
	s_add_i32 s57, s53, 16
	s_cmpk_lt_i32 s57, 0x2000
	s_movk_i32 s0, 0x3ff
	s_cselect_b32 s0, 0xff, s0
	s_and_b32 s1, s57, s0
	s_cmp_lg_u32 s1, s0
	s_cselect_b32 s60, 1.0, 0
	s_cselect_b32 s1, 1, 0
	s_add_i32 s1, s57, s1
	s_mul_i32 s0, s57, 0x1d00
	s_add_u32 s80, s28, s0
	s_addc_u32 s81, s29, 0
	s_mul_i32 s0, s1, 0x1d00
	s_add_u32 s82, s28, s0
	s_addc_u32 s83, s29, 0
	global_load_dwordx2 v[236:237], v250, s[80:81] offset:0
	global_load_dwordx2 v[238:239], v250, s[80:81] offset:512
	global_load_dwordx2 v[240:241], v250, s[80:81] offset:1024
	global_load_dwordx2 v[242:243], v250, s[82:83] offset:0
	global_load_dwordx2 v[244:245], v250, s[82:83] offset:512
	global_load_dwordx2 v[246:247], v250, s[82:83] offset:1024
	s_lshl_b32 s0, s57, 9
	s_add_u32 s0, s42, s0
	s_addc_u32 s1, s43, 0
	global_load_dwordx2 v[248:249], v250, s[0:1]
	ds_read_b128 v[22:25], v31 offset:12288
	ds_read_b128 v[26:29], v31 offset:32768
	s_waitcnt vmcnt(28)
	v_lshlrev_b32_e32 v134, 16, v0
	v_and_b32_e32 v0, 0xffff0000, v0
	v_lshlrev_b32_e32 v135, 16, v1
	v_and_b32_e32 v1, 0xffff0000, v1
	v_lshlrev_b32_e32 v136, 16, v2
	v_and_b32_e32 v2, 0xffff0000, v2
	v_lshlrev_b32_e32 v137, 16, v3
	v_and_b32_e32 v3, 0xffff0000, v3
	v_lshlrev_b32_e32 v138, 16, v4
	v_and_b32_e32 v4, 0xffff0000, v4
	v_lshlrev_b32_e32 v139, 16, v5
	v_and_b32_e32 v5, 0xffff0000, v5
	v_lshlrev_b32_e32 v140, 16, v6
	v_and_b32_e32 v6, 0xffff0000, v6
	v_lshlrev_b32_e32 v141, 16, v7
	v_and_b32_e32 v7, 0xffff0000, v7
	v_lshlrev_b32_e32 v142, 16, v8
	v_and_b32_e32 v8, 0xffff0000, v8
	v_lshlrev_b32_e32 v143, 16, v9
	v_and_b32_e32 v9, 0xffff0000, v9
	v_lshlrev_b32_e32 v144, 16, v10
	v_and_b32_e32 v10, 0xffff0000, v10
	v_lshlrev_b32_e32 v145, 16, v11
	v_and_b32_e32 v11, 0xffff0000, v11
	v_lshlrev_b32_e32 v146, 16, v12
	v_and_b32_e32 v12, 0xffff0000, v12
	v_lshlrev_b32_e32 v147, 16, v13
	v_and_b32_e32 v13, 0xffff0000, v13
	v_fma_f32 v140, s61, v140, -v134
	v_fma_f32 v6, s61, v6, -v0
	v_fma_f32 v141, s61, v141, -v135
	v_fma_f32 v7, s61, v7, -v1
	v_fmac_f32_e32 v134, v210, v140
	v_fmac_f32_e32 v0, v211, v6
	v_fmac_f32_e32 v135, v212, v141
	v_fmac_f32_e32 v1, v213, v7
	v_fma_f32 v142, s61, v142, -v136
	v_fma_f32 v8, s61, v8, -v2
	v_fma_f32 v143, s61, v143, -v137
	v_fma_f32 v9, s61, v9, -v3
	v_fmac_f32_e32 v136, v214, v142
	v_fmac_f32_e32 v2, v215, v8
	v_fmac_f32_e32 v137, v216, v143
	v_fmac_f32_e32 v3, v217, v9
	v_fma_f32 v144, s61, v144, -v138
	v_fma_f32 v10, s61, v10, -v4
	v_fma_f32 v145, s61, v145, -v139
	v_fma_f32 v11, s61, v11, -v5
	v_fmac_f32_e32 v138, v218, v144
	v_fmac_f32_e32 v4, v219, v10
	v_fmac_f32_e32 v139, v220, v145
	v_fmac_f32_e32 v5, v221, v11
	v_mul_f32_e32 v148, v198, v136
	v_mul_f32_e32 v149, v199, v2
	v_mul_f32_e32 v150, v200, v137
	v_mul_f32_e32 v151, v201, v3
	v_mul_f32_e32 v176, v148, v148
	v_fmac_f32_e32 v176, v149, v149
	v_fmac_f32_e32 v176, v150, v150
	v_fmac_f32_e32 v176, v151, v151
	s_waitcnt lgkmcnt(2)
	v_add_f32_e32 v18, v194, v18
	v_add_f32_e32 v19, v195, v19
	v_add_f32_e32 v20, v196, v20
	v_add_f32_e32 v21, v197, v21
	v_add_f32_dpp v176, v176, v176 quad_perm:[1,0,3,2] row_mask:0xf bank_mask:0xf bound_ctrl:1
	v_mul_f32_e32 v18, 0xbfb8aa3b, v18
	v_mul_f32_e32 v19, 0xbfb8aa3b, v19
	v_mul_f32_e32 v20, 0xbfb8aa3b, v20
	v_mul_f32_e32 v21, 0xbfb8aa3b, v21
	v_add_f32_dpp v176, v176, v176 quad_perm:[2,3,0,1] row_mask:0xf bank_mask:0xf bound_ctrl:1
	v_exp_f32_e32 v18, v18
	v_exp_f32_e32 v19, v19
	v_exp_f32_e32 v20, v20
	v_exp_f32_e32 v21, v21
	v_add_f32_dpp v176, v176, v176 row_half_mirror row_mask:0xf bank_mask:0xf bound_ctrl:1
	v_add_f32_e32 v18, 1.0, v18
	v_add_f32_e32 v19, 1.0, v19
	v_add_f32_e32 v20, 1.0, v20
	v_add_f32_e32 v21, 1.0, v21
	v_add_f32_dpp v176, v176, v176 row_mirror row_mask:0xf bank_mask:0xf bound_ctrl:1
	v_rcp_f32_e32 v18, v18
	v_rcp_f32_e32 v19, v19
	v_rcp_f32_e32 v20, v20
	v_rcp_f32_e32 v21, v21
	v_sqrt_f32_e32 v176, v176
	v_add_f32_e32 v14, v190, v14
	v_add_f32_e32 v15, v191, v15
	v_add_f32_e32 v16, v192, v16
	v_add_f32_e32 v17, v193, v17
	v_max_f32_e32 v176, 0x2b8cbccc, v176
	v_mul_f32_e32 v14, 0xbfb8aa3b, v14
	v_mul_f32_e32 v15, 0xbfb8aa3b, v15
	v_mul_f32_e32 v16, 0xbfb8aa3b, v16
	v_mul_f32_e32 v17, 0xbfb8aa3b, v17
	v_rcp_f32_e32 v178, v176
	v_exp_f32_e32 v14, v14
	v_exp_f32_e32 v15, v15
	v_exp_f32_e32 v16, v16
	v_exp_f32_e32 v17, v17
	v_add_f32_e32 v14, 1.0, v14
	v_add_f32_e32 v15, 1.0, v15
	v_add_f32_e32 v16, 1.0, v16
	v_add_f32_e32 v17, 1.0, v17
	v_rcp_f32_e32 v14, v14
	v_rcp_f32_e32 v15, v15
	v_rcp_f32_e32 v16, v16
	v_rcp_f32_e32 v17, v17
	v_mul_f32_e32 v14, 0xbf1b4598, v14
	v_mul_f32_e32 v15, 0xbf1b4598, v15
	v_mul_f32_e32 v16, 0xbf1b4598, v16
	v_mul_f32_e32 v17, 0xbf1b4598, v17
	v_mul_f32_e32 v14, 0x3fb8aa3b, v14
	v_mul_f32_e32 v15, 0x3fb8aa3b, v15
	v_mul_f32_e32 v16, 0x3fb8aa3b, v16
	v_mul_f32_e32 v17, 0x3fb8aa3b, v17
	v_exp_f32_e32 v14, v14
	v_exp_f32_e32 v15, v15
	v_exp_f32_e32 v16, v16
	v_exp_f32_e32 v17, v17
	v_add_f32_e32 v152, -1.0, v18
	v_add_f32_e32 v153, -1.0, v19
	v_add_f32_e32 v154, -1.0, v20
	v_add_f32_e32 v155, -1.0, v21
	v_fma_f32 v152, v202, v152, 1.0
	v_fma_f32 v153, v203, v153, 1.0
	v_fma_f32 v154, v204, v154, 1.0
	v_fma_f32 v155, v205, v155, 1.0
	v_mul_f32_e32 v152, v136, v152
	v_mul_f32_e32 v153, v2, v153
	v_mul_f32_e32 v154, v137, v154
	v_mul_f32_e32 v155, v3, v155
	v_mul_f32_e32 v156, v134, v152
	v_mul_f32_e32 v157, v0, v153
	v_mul_f32_e32 v158, v135, v154
	v_mul_f32_e32 v159, v1, v155
	v_mul_f32_e32 v177, v206, v156
	v_fmac_f32_e32 v177, v207, v157
	v_fmac_f32_e32 v177, v208, v158
	v_fmac_f32_e32 v177, v209, v159
	v_mul_f32_e32 v148, v148, v178
	v_mul_f32_e32 v149, v149, v178
	v_add_f32_dpp v177, v177, v177 quad_perm:[1,0,3,2] row_mask:0xf bank_mask:0xf bound_ctrl:1
	v_mul_f32_e32 v150, v150, v178
	v_mul_f32_e32 v151, v151, v178
	v_add_f32_dpp v177, v177, v177 quad_perm:[2,3,0,1] row_mask:0xf bank_mask:0xf bound_ctrl:1
	v_mul_f32_e32 v18, v18, v148
	v_mul_f32_e32 v19, v19, v149
	v_add_f32_dpp v177, v177, v177 row_half_mirror row_mask:0xf bank_mask:0xf bound_ctrl:1
	v_mul_f32_e32 v20, v20, v150
	v_mul_f32_e32 v21, v21, v151
	v_add_f32_dpp v177, v177, v177 row_mirror row_mask:0xf bank_mask:0xf bound_ctrl:1
	s_lshl_b32 s0, s58, 9
	s_add_u32 s62, s34, s0
	s_addc_u32 s63, s35, 0
	v_fmac_f32_e32 v146, v138, v177
	v_fmac_f32_e32 v12, v4, v177
	v_fmac_f32_e32 v147, v139, v177
	v_fmac_f32_e32 v13, v5, v177
	v_cvt_pk_bf16_f32 v72, v134, v0
	v_cvt_pk_bf16_f32 v73, v135, v1
	global_store_dwordx2 v250, v[72:73], s[62:63]
	v_cvt_pk_bf16_f32 v74, v14, v15
	v_cvt_pk_bf16_f32 v75, v16, v17
	s_add_u32 s0, s62, 0x500000
	s_addc_u32 s1, s63, 0
	global_store_dwordx2 v250, v[74:75], s[0:1]
	v_cvt_pk_bf16_f32 v180, v152, v153
	v_cvt_pk_bf16_f32 v181, v154, v155
	s_add_u32 s0, s62, 0xa00000
	s_addc_u32 s1, s63, 0
	global_store_dwordx2 v250, v[180:181], s[0:1]
	v_cvt_pk_bf16_f32 v72, v138, v4
	v_cvt_pk_bf16_f32 v73, v139, v5
	s_add_u32 s0, s62, 0xf00000
	s_addc_u32 s1, s63, 0
	global_store_dwordx2 v250, v[72:73], s[0:1]
	v_cvt_pk_bf16_f32 v74, v148, v149
	v_cvt_pk_bf16_f32 v75, v150, v151
	s_add_u32 s0, s62, 0x1400000
	s_addc_u32 s1, s63, 0
	global_store_dwordx2 v250, v[74:75], s[0:1]
	v_cvt_pk_bf16_f32 v180, v18, v19
	v_cvt_pk_bf16_f32 v181, v20, v21
	s_add_u32 s0, s62, 0x1900000
	s_addc_u32 s1, s63, 0
	global_store_dwordx2 v250, v[180:181], s[0:1]
	v_cvt_pk_bf16_f32 v72, v146, v12
	v_cvt_pk_bf16_f32 v73, v147, v13
	s_lshl_b32 s0, s58, 9
	s_add_u32 s0, s42, s0
	s_addc_u32 s1, s43, 0
	global_store_dwordx2 v250, v[72:73], s[0:1]
	ds_read_b128 v[14:17], v31 offset:16384
	ds_read_b128 v[18:21], v31 offset:36864
	s_waitcnt vmcnt(21)
	v_lshlrev_b32_e32 v134, 16, v222
	v_and_b32_e32 v222, 0xffff0000, v222
	v_lshlrev_b32_e32 v135, 16, v223
	v_and_b32_e32 v223, 0xffff0000, v223
	v_lshlrev_b32_e32 v136, 16, v224
	v_and_b32_e32 v224, 0xffff0000, v224
	v_lshlrev_b32_e32 v137, 16, v225
	v_and_b32_e32 v225, 0xffff0000, v225
	v_lshlrev_b32_e32 v138, 16, v226
	v_and_b32_e32 v226, 0xffff0000, v226
	v_lshlrev_b32_e32 v139, 16, v227
	v_and_b32_e32 v227, 0xffff0000, v227
	v_lshlrev_b32_e32 v140, 16, v228
	v_and_b32_e32 v228, 0xffff0000, v228
	v_lshlrev_b32_e32 v141, 16, v229
	v_and_b32_e32 v229, 0xffff0000, v229
	v_lshlrev_b32_e32 v142, 16, v230
	v_and_b32_e32 v230, 0xffff0000, v230
	v_lshlrev_b32_e32 v143, 16, v231
	v_and_b32_e32 v231, 0xffff0000, v231
	v_lshlrev_b32_e32 v144, 16, v232
	v_and_b32_e32 v232, 0xffff0000, v232
	v_lshlrev_b32_e32 v145, 16, v233
	v_and_b32_e32 v233, 0xffff0000, v233
	v_lshlrev_b32_e32 v146, 16, v234
	v_and_b32_e32 v234, 0xffff0000, v234
	v_lshlrev_b32_e32 v147, 16, v235
	v_and_b32_e32 v235, 0xffff0000, v235
	v_fma_f32 v140, s59, v140, -v134
	v_fma_f32 v228, s59, v228, -v222
	v_fma_f32 v141, s59, v141, -v135
	v_fma_f32 v229, s59, v229, -v223
	v_fmac_f32_e32 v134, v210, v140
	v_fmac_f32_e32 v222, v211, v228
	v_fmac_f32_e32 v135, v212, v141
	v_fmac_f32_e32 v223, v213, v229
	v_fma_f32 v142, s59, v142, -v136
	v_fma_f32 v230, s59, v230, -v224
	v_fma_f32 v143, s59, v143, -v137
	v_fma_f32 v231, s59, v231, -v225
	v_fmac_f32_e32 v136, v214, v142
	v_fmac_f32_e32 v224, v215, v230
	v_fmac_f32_e32 v137, v216, v143
	v_fmac_f32_e32 v225, v217, v231
	v_fma_f32 v144, s59, v144, -v138
	v_fma_f32 v232, s59, v232, -v226
	v_fma_f32 v145, s59, v145, -v139
	v_fma_f32 v233, s59, v233, -v227
	v_fmac_f32_e32 v138, v218, v144
	v_fmac_f32_e32 v226, v219, v232
	v_fmac_f32_e32 v139, v220, v145
	v_fmac_f32_e32 v227, v221, v233
	v_mul_f32_e32 v148, v198, v136
	v_mul_f32_e32 v149, v199, v224
	v_mul_f32_e32 v150, v200, v137
	v_mul_f32_e32 v151, v201, v225
	v_mul_f32_e32 v176, v148, v148
	v_fmac_f32_e32 v176, v149, v149
	v_fmac_f32_e32 v176, v150, v150
	v_fmac_f32_e32 v176, v151, v151
	s_waitcnt lgkmcnt(2)
	v_add_f32_e32 v26, v194, v26
	v_add_f32_e32 v27, v195, v27
	v_add_f32_e32 v28, v196, v28
	v_add_f32_e32 v29, v197, v29
	v_add_f32_dpp v176, v176, v176 quad_perm:[1,0,3,2] row_mask:0xf bank_mask:0xf bound_ctrl:1
	v_mul_f32_e32 v26, 0xbfb8aa3b, v26
	v_mul_f32_e32 v27, 0xbfb8aa3b, v27
	v_mul_f32_e32 v28, 0xbfb8aa3b, v28
	v_mul_f32_e32 v29, 0xbfb8aa3b, v29
	v_add_f32_dpp v176, v176, v176 quad_perm:[2,3,0,1] row_mask:0xf bank_mask:0xf bound_ctrl:1
	v_exp_f32_e32 v26, v26
	v_exp_f32_e32 v27, v27
	v_exp_f32_e32 v28, v28
	v_exp_f32_e32 v29, v29
	v_add_f32_dpp v176, v176, v176 row_half_mirror row_mask:0xf bank_mask:0xf bound_ctrl:1
	v_add_f32_e32 v26, 1.0, v26
	v_add_f32_e32 v27, 1.0, v27
	v_add_f32_e32 v28, 1.0, v28
	v_add_f32_e32 v29, 1.0, v29
	v_add_f32_dpp v176, v176, v176 row_mirror row_mask:0xf bank_mask:0xf bound_ctrl:1
	v_rcp_f32_e32 v26, v26
	v_rcp_f32_e32 v27, v27
	v_rcp_f32_e32 v28, v28
	v_rcp_f32_e32 v29, v29
	v_sqrt_f32_e32 v176, v176
	v_add_f32_e32 v22, v190, v22
	v_add_f32_e32 v23, v191, v23
	v_add_f32_e32 v24, v192, v24
	v_add_f32_e32 v25, v193, v25
	v_max_f32_e32 v176, 0x2b8cbccc, v176
	v_mul_f32_e32 v22, 0xbfb8aa3b, v22
	v_mul_f32_e32 v23, 0xbfb8aa3b, v23
	v_mul_f32_e32 v24, 0xbfb8aa3b, v24
	v_mul_f32_e32 v25, 0xbfb8aa3b, v25
	v_rcp_f32_e32 v178, v176
	v_exp_f32_e32 v22, v22
	v_exp_f32_e32 v23, v23
	v_exp_f32_e32 v24, v24
	v_exp_f32_e32 v25, v25
	v_add_f32_e32 v22, 1.0, v22
	v_add_f32_e32 v23, 1.0, v23
	v_add_f32_e32 v24, 1.0, v24
	v_add_f32_e32 v25, 1.0, v25
	v_rcp_f32_e32 v22, v22
	v_rcp_f32_e32 v23, v23
	v_rcp_f32_e32 v24, v24
	v_rcp_f32_e32 v25, v25
	v_mul_f32_e32 v22, 0xbf1b4598, v22
	v_mul_f32_e32 v23, 0xbf1b4598, v23
	v_mul_f32_e32 v24, 0xbf1b4598, v24
	v_mul_f32_e32 v25, 0xbf1b4598, v25
	v_mul_f32_e32 v22, 0x3fb8aa3b, v22
	v_mul_f32_e32 v23, 0x3fb8aa3b, v23
	v_mul_f32_e32 v24, 0x3fb8aa3b, v24
	v_mul_f32_e32 v25, 0x3fb8aa3b, v25
	v_exp_f32_e32 v22, v22
	v_exp_f32_e32 v23, v23
	v_exp_f32_e32 v24, v24
	v_exp_f32_e32 v25, v25
	v_add_f32_e32 v152, -1.0, v26
	v_add_f32_e32 v153, -1.0, v27
	v_add_f32_e32 v154, -1.0, v28
	v_add_f32_e32 v155, -1.0, v29
	v_fma_f32 v152, v202, v152, 1.0
	v_fma_f32 v153, v203, v153, 1.0
	v_fma_f32 v154, v204, v154, 1.0
	v_fma_f32 v155, v205, v155, 1.0
	v_mul_f32_e32 v152, v136, v152
	v_mul_f32_e32 v153, v224, v153
	v_mul_f32_e32 v154, v137, v154
	v_mul_f32_e32 v155, v225, v155
	v_mul_f32_e32 v156, v134, v152
	v_mul_f32_e32 v157, v222, v153
	v_mul_f32_e32 v158, v135, v154
	v_mul_f32_e32 v159, v223, v155
	v_mul_f32_e32 v177, v206, v156
	v_fmac_f32_e32 v177, v207, v157
	v_fmac_f32_e32 v177, v208, v158
	v_fmac_f32_e32 v177, v209, v159
	v_mul_f32_e32 v148, v148, v178
	v_mul_f32_e32 v149, v149, v178
	v_add_f32_dpp v177, v177, v177 quad_perm:[1,0,3,2] row_mask:0xf bank_mask:0xf bound_ctrl:1
	v_mul_f32_e32 v150, v150, v178
	v_mul_f32_e32 v151, v151, v178
	v_add_f32_dpp v177, v177, v177 quad_perm:[2,3,0,1] row_mask:0xf bank_mask:0xf bound_ctrl:1
	v_mul_f32_e32 v26, v26, v148
	v_mul_f32_e32 v27, v27, v149
	v_add_f32_dpp v177, v177, v177 row_half_mirror row_mask:0xf bank_mask:0xf bound_ctrl:1
	v_mul_f32_e32 v28, v28, v150
	v_mul_f32_e32 v29, v29, v151
	v_add_f32_dpp v177, v177, v177 row_mirror row_mask:0xf bank_mask:0xf bound_ctrl:1
	s_lshl_b32 s0, s56, 9
	s_add_u32 s62, s34, s0
	s_addc_u32 s63, s35, 0
	v_fmac_f32_e32 v146, v138, v177
	v_fmac_f32_e32 v234, v226, v177
	v_fmac_f32_e32 v147, v139, v177
	v_fmac_f32_e32 v235, v227, v177
	v_cvt_pk_bf16_f32 v72, v134, v222
	v_cvt_pk_bf16_f32 v73, v135, v223
	global_store_dwordx2 v250, v[72:73], s[62:63]
	v_cvt_pk_bf16_f32 v74, v22, v23
	v_cvt_pk_bf16_f32 v75, v24, v25
	s_add_u32 s0, s62, 0x500000
	s_addc_u32 s1, s63, 0
	global_store_dwordx2 v250, v[74:75], s[0:1]
	v_cvt_pk_bf16_f32 v180, v152, v153
	v_cvt_pk_bf16_f32 v181, v154, v155
	s_add_u32 s0, s62, 0xa00000
	s_addc_u32 s1, s63, 0
	global_store_dwordx2 v250, v[180:181], s[0:1]
	v_cvt_pk_bf16_f32 v72, v138, v226
	v_cvt_pk_bf16_f32 v73, v139, v227
	s_add_u32 s0, s62, 0xf00000
	s_addc_u32 s1, s63, 0
	global_store_dwordx2 v250, v[72:73], s[0:1]
	v_cvt_pk_bf16_f32 v74, v148, v149
	v_cvt_pk_bf16_f32 v75, v150, v151
	s_add_u32 s0, s62, 0x1400000
	s_addc_u32 s1, s63, 0
	global_store_dwordx2 v250, v[74:75], s[0:1]
	v_cvt_pk_bf16_f32 v180, v26, v27
	v_cvt_pk_bf16_f32 v181, v28, v29
	s_add_u32 s0, s62, 0x1900000
	s_addc_u32 s1, s63, 0
	global_store_dwordx2 v250, v[180:181], s[0:1]
	v_cvt_pk_bf16_f32 v72, v146, v234
	v_cvt_pk_bf16_f32 v73, v147, v235
	s_lshl_b32 s0, s56, 9
	s_add_u32 s0, s42, s0
	s_addc_u32 s1, s43, 0
	global_store_dwordx2 v250, v[72:73], s[0:1]
	s_waitcnt vmcnt(14)
	v_lshlrev_b32_e32 v134, 16, v236
	v_and_b32_e32 v236, 0xffff0000, v236
	v_lshlrev_b32_e32 v135, 16, v237
	v_and_b32_e32 v237, 0xffff0000, v237
	v_lshlrev_b32_e32 v136, 16, v238
	v_and_b32_e32 v238, 0xffff0000, v238
	v_lshlrev_b32_e32 v137, 16, v239
	v_and_b32_e32 v239, 0xffff0000, v239
	v_lshlrev_b32_e32 v138, 16, v240
	v_and_b32_e32 v240, 0xffff0000, v240
	v_lshlrev_b32_e32 v139, 16, v241
	v_and_b32_e32 v241, 0xffff0000, v241
	v_lshlrev_b32_e32 v140, 16, v242
	v_and_b32_e32 v242, 0xffff0000, v242
	v_lshlrev_b32_e32 v141, 16, v243
	v_and_b32_e32 v243, 0xffff0000, v243
	v_lshlrev_b32_e32 v142, 16, v244
	v_and_b32_e32 v244, 0xffff0000, v244
	v_lshlrev_b32_e32 v143, 16, v245
	v_and_b32_e32 v245, 0xffff0000, v245
	v_lshlrev_b32_e32 v144, 16, v246
	v_and_b32_e32 v246, 0xffff0000, v246
	v_lshlrev_b32_e32 v145, 16, v247
	v_and_b32_e32 v247, 0xffff0000, v247
	v_lshlrev_b32_e32 v146, 16, v248
	v_and_b32_e32 v248, 0xffff0000, v248
	v_lshlrev_b32_e32 v147, 16, v249
	v_and_b32_e32 v249, 0xffff0000, v249
	v_fma_f32 v140, s60, v140, -v134
	v_fma_f32 v242, s60, v242, -v236
	v_fma_f32 v141, s60, v141, -v135
	v_fma_f32 v243, s60, v243, -v237
	v_fmac_f32_e32 v134, v210, v140
	v_fmac_f32_e32 v236, v211, v242
	v_fmac_f32_e32 v135, v212, v141
	v_fmac_f32_e32 v237, v213, v243
	v_fma_f32 v142, s60, v142, -v136
	v_fma_f32 v244, s60, v244, -v238
	v_fma_f32 v143, s60, v143, -v137
	v_fma_f32 v245, s60, v245, -v239
	v_fmac_f32_e32 v136, v214, v142
	v_fmac_f32_e32 v238, v215, v244
	v_fmac_f32_e32 v137, v216, v143
	v_fmac_f32_e32 v239, v217, v245
	v_fma_f32 v144, s60, v144, -v138
	v_fma_f32 v246, s60, v246, -v240
	v_fma_f32 v145, s60, v145, -v139
	v_fma_f32 v247, s60, v247, -v241
	v_fmac_f32_e32 v138, v218, v144
	v_fmac_f32_e32 v240, v219, v246
	v_fmac_f32_e32 v139, v220, v145
	v_fmac_f32_e32 v241, v221, v247
	v_mul_f32_e32 v148, v198, v136
	v_mul_f32_e32 v149, v199, v238
	v_mul_f32_e32 v150, v200, v137
	v_mul_f32_e32 v151, v201, v239
	v_mul_f32_e32 v176, v148, v148
	v_fmac_f32_e32 v176, v149, v149
	v_fmac_f32_e32 v176, v150, v150
	v_fmac_f32_e32 v176, v151, v151
	s_waitcnt lgkmcnt(0)
	v_add_f32_e32 v18, v194, v18
	v_add_f32_e32 v19, v195, v19
	v_add_f32_e32 v20, v196, v20
	v_add_f32_e32 v21, v197, v21
	v_add_f32_dpp v176, v176, v176 quad_perm:[1,0,3,2] row_mask:0xf bank_mask:0xf bound_ctrl:1
	v_mul_f32_e32 v18, 0xbfb8aa3b, v18
	v_mul_f32_e32 v19, 0xbfb8aa3b, v19
	v_mul_f32_e32 v20, 0xbfb8aa3b, v20
	v_mul_f32_e32 v21, 0xbfb8aa3b, v21
	v_add_f32_dpp v176, v176, v176 quad_perm:[2,3,0,1] row_mask:0xf bank_mask:0xf bound_ctrl:1
	v_exp_f32_e32 v18, v18
	v_exp_f32_e32 v19, v19
	v_exp_f32_e32 v20, v20
	v_exp_f32_e32 v21, v21
	v_add_f32_dpp v176, v176, v176 row_half_mirror row_mask:0xf bank_mask:0xf bound_ctrl:1
	v_add_f32_e32 v18, 1.0, v18
	v_add_f32_e32 v19, 1.0, v19
	v_add_f32_e32 v20, 1.0, v20
	v_add_f32_e32 v21, 1.0, v21
	v_add_f32_dpp v176, v176, v176 row_mirror row_mask:0xf bank_mask:0xf bound_ctrl:1
	v_rcp_f32_e32 v18, v18
	v_rcp_f32_e32 v19, v19
	v_rcp_f32_e32 v20, v20
	v_rcp_f32_e32 v21, v21
	v_sqrt_f32_e32 v176, v176
	v_add_f32_e32 v14, v190, v14
	v_add_f32_e32 v15, v191, v15
	v_add_f32_e32 v16, v192, v16
	v_add_f32_e32 v17, v193, v17
	v_max_f32_e32 v176, 0x2b8cbccc, v176
	v_mul_f32_e32 v14, 0xbfb8aa3b, v14
	v_mul_f32_e32 v15, 0xbfb8aa3b, v15
	v_mul_f32_e32 v16, 0xbfb8aa3b, v16
	v_mul_f32_e32 v17, 0xbfb8aa3b, v17
	v_rcp_f32_e32 v178, v176
	v_exp_f32_e32 v14, v14
	v_exp_f32_e32 v15, v15
	v_exp_f32_e32 v16, v16
	v_exp_f32_e32 v17, v17
	v_add_f32_e32 v14, 1.0, v14
	v_add_f32_e32 v15, 1.0, v15
	v_add_f32_e32 v16, 1.0, v16
	v_add_f32_e32 v17, 1.0, v17
	v_rcp_f32_e32 v14, v14
	v_rcp_f32_e32 v15, v15
	v_rcp_f32_e32 v16, v16
	v_rcp_f32_e32 v17, v17
	v_mul_f32_e32 v14, 0xbf1b4598, v14
	v_mul_f32_e32 v15, 0xbf1b4598, v15
	v_mul_f32_e32 v16, 0xbf1b4598, v16
	v_mul_f32_e32 v17, 0xbf1b4598, v17
	v_mul_f32_e32 v14, 0x3fb8aa3b, v14
	v_mul_f32_e32 v15, 0x3fb8aa3b, v15
	v_mul_f32_e32 v16, 0x3fb8aa3b, v16
	v_mul_f32_e32 v17, 0x3fb8aa3b, v17
	v_exp_f32_e32 v14, v14
	v_exp_f32_e32 v15, v15
	v_exp_f32_e32 v16, v16
	v_exp_f32_e32 v17, v17
	v_add_f32_e32 v152, -1.0, v18
	v_add_f32_e32 v153, -1.0, v19
	v_add_f32_e32 v154, -1.0, v20
	v_add_f32_e32 v155, -1.0, v21
	v_fma_f32 v152, v202, v152, 1.0
	v_fma_f32 v153, v203, v153, 1.0
	v_fma_f32 v154, v204, v154, 1.0
	v_fma_f32 v155, v205, v155, 1.0
	v_mul_f32_e32 v152, v136, v152
	v_mul_f32_e32 v153, v238, v153
	v_mul_f32_e32 v154, v137, v154
	v_mul_f32_e32 v155, v239, v155
	v_mul_f32_e32 v156, v134, v152
	v_mul_f32_e32 v157, v236, v153
	v_mul_f32_e32 v158, v135, v154
	v_mul_f32_e32 v159, v237, v155
	v_mul_f32_e32 v177, v206, v156
	v_fmac_f32_e32 v177, v207, v157
	v_fmac_f32_e32 v177, v208, v158
	v_fmac_f32_e32 v177, v209, v159
	v_mul_f32_e32 v148, v148, v178
	v_mul_f32_e32 v149, v149, v178
	v_add_f32_dpp v177, v177, v177 quad_perm:[1,0,3,2] row_mask:0xf bank_mask:0xf bound_ctrl:1
	v_mul_f32_e32 v150, v150, v178
	v_mul_f32_e32 v151, v151, v178
	v_add_f32_dpp v177, v177, v177 quad_perm:[2,3,0,1] row_mask:0xf bank_mask:0xf bound_ctrl:1
	v_mul_f32_e32 v18, v18, v148
	v_mul_f32_e32 v19, v19, v149
	v_add_f32_dpp v177, v177, v177 row_half_mirror row_mask:0xf bank_mask:0xf bound_ctrl:1
	v_mul_f32_e32 v20, v20, v150
	v_mul_f32_e32 v21, v21, v151
	v_add_f32_dpp v177, v177, v177 row_mirror row_mask:0xf bank_mask:0xf bound_ctrl:1
	s_lshl_b32 s0, s57, 9
	s_add_u32 s62, s34, s0
	s_addc_u32 s63, s35, 0
	v_fmac_f32_e32 v146, v138, v177
	v_fmac_f32_e32 v248, v240, v177
	v_fmac_f32_e32 v147, v139, v177
	v_fmac_f32_e32 v249, v241, v177
	v_cvt_pk_bf16_f32 v72, v134, v236
	v_cvt_pk_bf16_f32 v73, v135, v237
	global_store_dwordx2 v250, v[72:73], s[62:63]
	v_cvt_pk_bf16_f32 v74, v14, v15
	v_cvt_pk_bf16_f32 v75, v16, v17
	s_add_u32 s0, s62, 0x500000
	s_addc_u32 s1, s63, 0
	global_store_dwordx2 v250, v[74:75], s[0:1]
	v_cvt_pk_bf16_f32 v180, v152, v153
	v_cvt_pk_bf16_f32 v181, v154, v155
	s_add_u32 s0, s62, 0xa00000
	s_addc_u32 s1, s63, 0
	global_store_dwordx2 v250, v[180:181], s[0:1]
	v_cvt_pk_bf16_f32 v72, v138, v240
	v_cvt_pk_bf16_f32 v73, v139, v241
	s_add_u32 s0, s62, 0xf00000
	s_addc_u32 s1, s63, 0
	global_store_dwordx2 v250, v[72:73], s[0:1]
	v_cvt_pk_bf16_f32 v74, v148, v149
	v_cvt_pk_bf16_f32 v75, v150, v151
	s_add_u32 s0, s62, 0x1400000
	s_addc_u32 s1, s63, 0
	global_store_dwordx2 v250, v[74:75], s[0:1]
	v_cvt_pk_bf16_f32 v180, v18, v19
	v_cvt_pk_bf16_f32 v181, v20, v21
	s_add_u32 s0, s62, 0x1900000
	s_addc_u32 s1, s63, 0
	global_store_dwordx2 v250, v[180:181], s[0:1]
	v_cvt_pk_bf16_f32 v72, v146, v248
	v_cvt_pk_bf16_f32 v73, v147, v249
	s_lshl_b32 s0, s57, 9
	s_add_u32 s0, s42, s0
	s_addc_u32 s1, s43, 0
	global_store_dwordx2 v250, v[72:73], s[0:1]
	s_branch .LBB0_476
